# DM1: GEMM K-loops: LDS-DMA issue rebalanced 4/4 -> 3/5 between the 16-read and the 8-read load segments (last DMA of each SP1 segment issued at the start of the following SP2 segment; vmcnt 8->7); on
# baseline (speedup 1.0000x reference)
.LBB0_287:
	ds_read_b128 v[136:139], v2
	ds_read_b128 v[140:143], v2 offset:1024
	ds_read_b128 v[144:147], v2 offset:2048
	ds_read_b128 v[148:151], v2 offset:3072
	ds_read_b128 v[152:155], v132
	ds_read_b128 v[156:159], v132 offset:1024
	ds_read_b128 v[160:163], v132 offset:2048
	ds_read_b128 v[164:167], v132 offset:3072
	s_cmp_eq_u32 s82, s72
	s_cselect_b32 s17, s51, s53
	s_cselect_b32 s16, s50, s52
	s_cselect_b32 s21, s15, s27
	s_cselect_b32 s20, s14, s26
	s_add_u32 s8, s26, 0xffffff80
	s_addc_u32 s9, s27, -1
	s_mov_b32 m0, s42
	s_mov_b64 s[18:19], s[8:9]
	ds_read_b128 v[168:171], v199 offset:8192
	ds_read_b128 v[172:175], v199 offset:9216
	ds_read_b128 v[176:179], v199 offset:10240
	ds_read_b128 v[180:183], v199 offset:11264
	ds_read_b128 v[184:187], v199 offset:12288
	ds_read_b128 v[188:191], v199 offset:13312
	ds_read_b128 v[202:205], v199 offset:14336
	ds_read_b128 v[206:209], v199 offset:15360
	s_add_u32 s8, s8, s54
	global_load_lds_dwordx4 v194, s[18:19]
	s_mov_b32 m0, s43
	s_addc_u32 s9, s9, s55
	global_load_lds_dwordx4 v195, s[18:19]
	s_mov_b32 m0, s44
	s_add_u32 s18, s16, 0x80
	global_load_lds_dwordx4 v194, s[8:9]
	s_addc_u32 s19, s17, 0
	s_mov_b64 s[100:101], s[8:9]
	s_waitcnt vmcnt(7)
	s_waitcnt lgkmcnt(0)
	s_barrier
	s_setprio 1
	s_waitcnt lgkmcnt(0)
	v_mfma_f32_16x16x32_bf16 v[4:7], v[136:139], v[168:171], v[4:7]
	v_mfma_f32_16x16x32_bf16 v[4:7], v[140:143], v[172:175], v[4:7]
	v_mfma_f32_16x16x32_bf16 v[8:11], v[144:147], v[168:171], v[8:11]
	v_mfma_f32_16x16x32_bf16 v[8:11], v[148:151], v[172:175], v[8:11]
	v_mfma_f32_16x16x32_bf16 v[12:15], v[136:139], v[176:179], v[12:15]
	v_mfma_f32_16x16x32_bf16 v[12:15], v[140:143], v[180:183], v[12:15]
	v_mfma_f32_16x16x32_bf16 v[16:19], v[144:147], v[176:179], v[16:19]
	v_mfma_f32_16x16x32_bf16 v[16:19], v[148:151], v[180:183], v[16:19]
	v_mfma_f32_16x16x32_bf16 v[20:23], v[136:139], v[184:187], v[20:23]
	v_mfma_f32_16x16x32_bf16 v[20:23], v[140:143], v[188:191], v[20:23]
	v_mfma_f32_16x16x32_bf16 v[24:27], v[144:147], v[184:187], v[24:27]
	v_mfma_f32_16x16x32_bf16 v[24:27], v[148:151], v[188:191], v[24:27]
	v_mfma_f32_16x16x32_bf16 v[28:31], v[136:139], v[202:205], v[28:31]
	v_mfma_f32_16x16x32_bf16 v[28:31], v[140:143], v[206:209], v[28:31]
	v_mfma_f32_16x16x32_bf16 v[32:35], v[144:147], v[202:205], v[32:35]
	v_mfma_f32_16x16x32_bf16 v[32:35], v[148:151], v[206:209], v[32:35]
	s_setprio 0
	s_setprio 1
	v_mfma_f32_16x16x32_bf16 v[36:39], v[152:155], v[168:171], v[36:39]
	v_mfma_f32_16x16x32_bf16 v[36:39], v[156:159], v[172:175], v[36:39]
	v_mfma_f32_16x16x32_bf16 v[40:43], v[160:163], v[168:171], v[40:43]
	v_mfma_f32_16x16x32_bf16 v[40:43], v[164:167], v[172:175], v[40:43]
	v_mfma_f32_16x16x32_bf16 v[44:47], v[152:155], v[176:179], v[44:47]
	v_mfma_f32_16x16x32_bf16 v[44:47], v[156:159], v[180:183], v[44:47]
	v_mfma_f32_16x16x32_bf16 v[48:51], v[160:163], v[176:179], v[48:51]
	v_mfma_f32_16x16x32_bf16 v[48:51], v[164:167], v[180:183], v[48:51]
	v_mfma_f32_16x16x32_bf16 v[52:55], v[152:155], v[184:187], v[52:55]
	v_mfma_f32_16x16x32_bf16 v[52:55], v[156:159], v[188:191], v[52:55]
	v_mfma_f32_16x16x32_bf16 v[56:59], v[160:163], v[184:187], v[56:59]
	v_mfma_f32_16x16x32_bf16 v[56:59], v[164:167], v[188:191], v[56:59]
	v_mfma_f32_16x16x32_bf16 v[60:63], v[152:155], v[202:205], v[60:63]
	v_mfma_f32_16x16x32_bf16 v[60:63], v[156:159], v[206:209], v[60:63]
	v_mfma_f32_16x16x32_bf16 v[64:67], v[160:163], v[202:205], v[64:67]
	v_mfma_f32_16x16x32_bf16 v[64:67], v[164:167], v[206:209], v[64:67]
	s_setprio 0
	s_barrier
	s_mov_b32 m0, s45
	s_nop 0
	global_load_lds_dwordx4 v195, s[100:101]
	s_mov_b32 m0, s46
	s_mov_b64 s[8:9], s[16:17]
	ds_read_b128 v[168:171], v199 offset:24576
	ds_read_b128 v[172:175], v199 offset:25600
	ds_read_b128 v[176:179], v199 offset:26624
	ds_read_b128 v[180:183], v199 offset:27648
	ds_read_b128 v[184:187], v199 offset:28672
	ds_read_b128 v[188:191], v199 offset:29696
	ds_read_b128 v[202:205], v199 offset:30720
	ds_read_b128 v[206:209], v199 offset:31744
	s_nop 0
	global_load_lds_dwordx4 v201, s[8:9]
	s_mov_b32 m0, s47
	s_nop 0
	global_load_lds_dwordx4 v200, s[8:9]
	s_add_u32 s8, s16, s54
	s_addc_u32 s9, s17, s55
	s_mov_b32 m0, s30
	s_nop 0
	global_load_lds_dwordx4 v201, s[8:9]
	s_mov_b32 m0, s31
	s_nop 0
	global_load_lds_dwordx4 v200, s[8:9]
	s_waitcnt vmcnt(6)
	s_waitcnt lgkmcnt(0)
	s_barrier
	s_setprio 1
	s_waitcnt lgkmcnt(0)
	v_mfma_f32_16x16x32_bf16 v[68:71], v[136:139], v[168:171], v[68:71]
	v_mfma_f32_16x16x32_bf16 v[68:71], v[140:143], v[172:175], v[68:71]
	v_mfma_f32_16x16x32_bf16 v[72:75], v[144:147], v[168:171], v[72:75]
	v_mfma_f32_16x16x32_bf16 v[72:75], v[148:151], v[172:175], v[72:75]
	v_mfma_f32_16x16x32_bf16 v[76:79], v[136:139], v[176:179], v[76:79]
	v_mfma_f32_16x16x32_bf16 v[76:79], v[140:143], v[180:183], v[76:79]
	v_mfma_f32_16x16x32_bf16 v[80:83], v[144:147], v[176:179], v[80:83]
	v_mfma_f32_16x16x32_bf16 v[80:83], v[148:151], v[180:183], v[80:83]
	v_mfma_f32_16x16x32_bf16 v[84:87], v[136:139], v[184:187], v[84:87]
	v_mfma_f32_16x16x32_bf16 v[84:87], v[140:143], v[188:191], v[84:87]
	v_mfma_f32_16x16x32_bf16 v[88:91], v[144:147], v[184:187], v[88:91]
	v_mfma_f32_16x16x32_bf16 v[88:91], v[148:151], v[188:191], v[88:91]
	v_mfma_f32_16x16x32_bf16 v[92:95], v[136:139], v[202:205], v[92:95]
	v_mfma_f32_16x16x32_bf16 v[92:95], v[140:143], v[206:209], v[92:95]
	v_mfma_f32_16x16x32_bf16 v[96:99], v[144:147], v[202:205], v[96:99]
	v_mfma_f32_16x16x32_bf16 v[96:99], v[148:151], v[206:209], v[96:99]
	s_setprio 0
	s_setprio 1
	v_mfma_f32_16x16x32_bf16 v[100:103], v[152:155], v[168:171], v[100:103]
	v_mfma_f32_16x16x32_bf16 v[100:103], v[156:159], v[172:175], v[100:103]
	v_mfma_f32_16x16x32_bf16 v[104:107], v[160:163], v[168:171], v[104:107]
	v_mfma_f32_16x16x32_bf16 v[104:107], v[164:167], v[172:175], v[104:107]
	v_mfma_f32_16x16x32_bf16 v[108:111], v[152:155], v[176:179], v[108:111]
	v_mfma_f32_16x16x32_bf16 v[108:111], v[156:159], v[180:183], v[108:111]
	v_mfma_f32_16x16x32_bf16 v[112:115], v[160:163], v[176:179], v[112:115]
	v_mfma_f32_16x16x32_bf16 v[112:115], v[164:167], v[180:183], v[112:115]
	v_mfma_f32_16x16x32_bf16 v[116:119], v[152:155], v[184:187], v[116:119]
	v_mfma_f32_16x16x32_bf16 v[116:119], v[156:159], v[188:191], v[116:119]
	v_mfma_f32_16x16x32_bf16 v[120:123], v[160:163], v[184:187], v[120:123]
	v_mfma_f32_16x16x32_bf16 v[120:123], v[164:167], v[188:191], v[120:123]
	v_mfma_f32_16x16x32_bf16 v[124:127], v[152:155], v[202:205], v[124:127]
	v_mfma_f32_16x16x32_bf16 v[124:127], v[156:159], v[206:209], v[124:127]
	v_mfma_f32_16x16x32_bf16 v[128:131], v[160:163], v[202:205], v[128:131]
	v_mfma_f32_16x16x32_bf16 v[128:131], v[164:167], v[206:209], v[128:131]
	s_setprio 0
	s_barrier
	ds_read_b128 v[136:139], v133
	ds_read_b128 v[140:143], v133 offset:1024
	ds_read_b128 v[144:147], v133 offset:2048
	ds_read_b128 v[148:151], v133 offset:3072
	ds_read_b128 v[152:155], v134
	ds_read_b128 v[156:159], v134 offset:1024
	ds_read_b128 v[160:163], v134 offset:2048
	ds_read_b128 v[164:167], v134 offset:3072
	s_mov_b32 m0, s85
	s_mov_b64 s[8:9], s[20:21]
	ds_read_b128 v[168:171], v199 offset:40960
	ds_read_b128 v[172:175], v199 offset:41984
	ds_read_b128 v[176:179], v199 offset:43008
	ds_read_b128 v[180:183], v199 offset:44032
	ds_read_b128 v[184:187], v199 offset:45056
	ds_read_b128 v[188:191], v199 offset:46080
	ds_read_b128 v[202:205], v199 offset:47104
	ds_read_b128 v[206:209], v199 offset:48128
	s_nop 0
	global_load_lds_dwordx4 v194, s[8:9]
	s_mov_b32 m0, s86
	s_nop 0
	global_load_lds_dwordx4 v195, s[8:9]
	s_add_u32 s8, s20, s54
	s_addc_u32 s9, s21, s55
	s_mov_b32 m0, s87
	s_nop 0
	global_load_lds_dwordx4 v194, s[8:9]
	s_mov_b64 s[100:101], s[8:9]
	s_waitcnt vmcnt(7)
	s_waitcnt lgkmcnt(0)
	s_barrier
	s_setprio 1
	s_waitcnt lgkmcnt(0)
	v_mfma_f32_16x16x32_bf16 v[4:7], v[136:139], v[168:171], v[4:7]
	v_mfma_f32_16x16x32_bf16 v[4:7], v[140:143], v[172:175], v[4:7]
	v_mfma_f32_16x16x32_bf16 v[8:11], v[144:147], v[168:171], v[8:11]
	v_mfma_f32_16x16x32_bf16 v[8:11], v[148:151], v[172:175], v[8:11]
	v_mfma_f32_16x16x32_bf16 v[12:15], v[136:139], v[176:179], v[12:15]
	v_mfma_f32_16x16x32_bf16 v[12:15], v[140:143], v[180:183], v[12:15]
	v_mfma_f32_16x16x32_bf16 v[16:19], v[144:147], v[176:179], v[16:19]
	v_mfma_f32_16x16x32_bf16 v[16:19], v[148:151], v[180:183], v[16:19]
	v_mfma_f32_16x16x32_bf16 v[20:23], v[136:139], v[184:187], v[20:23]
	v_mfma_f32_16x16x32_bf16 v[20:23], v[140:143], v[188:191], v[20:23]
	v_mfma_f32_16x16x32_bf16 v[24:27], v[144:147], v[184:187], v[24:27]
	v_mfma_f32_16x16x32_bf16 v[24:27], v[148:151], v[188:191], v[24:27]
	v_mfma_f32_16x16x32_bf16 v[28:31], v[136:139], v[202:205], v[28:31]
	v_mfma_f32_16x16x32_bf16 v[28:31], v[140:143], v[206:209], v[28:31]
	v_mfma_f32_16x16x32_bf16 v[32:35], v[144:147], v[202:205], v[32:35]
	v_mfma_f32_16x16x32_bf16 v[32:35], v[148:151], v[206:209], v[32:35]
	s_setprio 0
	s_setprio 1
	v_mfma_f32_16x16x32_bf16 v[36:39], v[152:155], v[168:171], v[36:39]
	v_mfma_f32_16x16x32_bf16 v[36:39], v[156:159], v[172:175], v[36:39]
	v_mfma_f32_16x16x32_bf16 v[40:43], v[160:163], v[168:171], v[40:43]
	v_mfma_f32_16x16x32_bf16 v[40:43], v[164:167], v[172:175], v[40:43]
	v_mfma_f32_16x16x32_bf16 v[44:47], v[152:155], v[176:179], v[44:47]
	v_mfma_f32_16x16x32_bf16 v[44:47], v[156:159], v[180:183], v[44:47]
	v_mfma_f32_16x16x32_bf16 v[48:51], v[160:163], v[176:179], v[48:51]
	v_mfma_f32_16x16x32_bf16 v[48:51], v[164:167], v[180:183], v[48:51]
	v_mfma_f32_16x16x32_bf16 v[52:55], v[152:155], v[184:187], v[52:55]
	v_mfma_f32_16x16x32_bf16 v[52:55], v[156:159], v[188:191], v[52:55]
	v_mfma_f32_16x16x32_bf16 v[56:59], v[160:163], v[184:187], v[56:59]
	v_mfma_f32_16x16x32_bf16 v[56:59], v[164:167], v[188:191], v[56:59]
	v_mfma_f32_16x16x32_bf16 v[60:63], v[152:155], v[202:205], v[60:63]
	v_mfma_f32_16x16x32_bf16 v[60:63], v[156:159], v[206:209], v[60:63]
	v_mfma_f32_16x16x32_bf16 v[64:67], v[160:163], v[202:205], v[64:67]
	v_mfma_f32_16x16x32_bf16 v[64:67], v[164:167], v[206:209], v[64:67]
	s_setprio 0
	s_barrier
	s_mov_b32 m0, s88
	s_nop 0
	global_load_lds_dwordx4 v195, s[100:101]
	s_mov_b32 m0, s48
	s_mov_b64 s[8:9], s[18:19]
	ds_read_b128 v[168:171], v199 offset:57344
	ds_read_b128 v[172:175], v199 offset:58368
	ds_read_b128 v[176:179], v199 offset:59392
	ds_read_b128 v[180:183], v199 offset:60416
	ds_read_b128 v[184:187], v199 offset:61440
	ds_read_b128 v[188:191], v199 offset:62464
	ds_read_b128 v[202:205], v199 offset:63488
	ds_read_b128 v[206:209], v199 offset:64512
	s_nop 0
	global_load_lds_dwordx4 v201, s[8:9]
	s_mov_b32 m0, s49
	s_nop 0
	global_load_lds_dwordx4 v200, s[8:9]
	s_add_u32 s8, s18, s54
	s_addc_u32 s9, s19, s55
	s_mov_b32 m0, s28
	s_nop 0
	global_load_lds_dwordx4 v201, s[8:9]
	s_mov_b32 m0, s29
	s_nop 0
	global_load_lds_dwordx4 v200, s[8:9]
	s_waitcnt vmcnt(6)
	s_waitcnt lgkmcnt(0)
	s_barrier
	s_setprio 1
	s_waitcnt lgkmcnt(0)
	v_mfma_f32_16x16x32_bf16 v[68:71], v[136:139], v[168:171], v[68:71]
	v_mfma_f32_16x16x32_bf16 v[68:71], v[140:143], v[172:175], v[68:71]
	v_mfma_f32_16x16x32_bf16 v[72:75], v[144:147], v[168:171], v[72:75]
	v_mfma_f32_16x16x32_bf16 v[72:75], v[148:151], v[172:175], v[72:75]
	v_mfma_f32_16x16x32_bf16 v[76:79], v[136:139], v[176:179], v[76:79]
	v_mfma_f32_16x16x32_bf16 v[76:79], v[140:143], v[180:183], v[76:79]
	v_mfma_f32_16x16x32_bf16 v[80:83], v[144:147], v[176:179], v[80:83]
	v_mfma_f32_16x16x32_bf16 v[80:83], v[148:151], v[180:183], v[80:83]
	v_mfma_f32_16x16x32_bf16 v[84:87], v[136:139], v[184:187], v[84:87]
	v_mfma_f32_16x16x32_bf16 v[84:87], v[140:143], v[188:191], v[84:87]
	v_mfma_f32_16x16x32_bf16 v[88:91], v[144:147], v[184:187], v[88:91]
	v_mfma_f32_16x16x32_bf16 v[88:91], v[148:151], v[188:191], v[88:91]
	v_mfma_f32_16x16x32_bf16 v[92:95], v[136:139], v[202:205], v[92:95]
	v_mfma_f32_16x16x32_bf16 v[92:95], v[140:143], v[206:209], v[92:95]
	v_mfma_f32_16x16x32_bf16 v[96:99], v[144:147], v[202:205], v[96:99]
	v_mfma_f32_16x16x32_bf16 v[96:99], v[148:151], v[206:209], v[96:99]
	s_setprio 0
	s_setprio 1
	v_mfma_f32_16x16x32_bf16 v[100:103], v[152:155], v[168:171], v[100:103]
	v_mfma_f32_16x16x32_bf16 v[100:103], v[156:159], v[172:175], v[100:103]
	v_mfma_f32_16x16x32_bf16 v[104:107], v[160:163], v[168:171], v[104:107]
	v_mfma_f32_16x16x32_bf16 v[104:107], v[164:167], v[172:175], v[104:107]
	v_mfma_f32_16x16x32_bf16 v[108:111], v[152:155], v[176:179], v[108:111]
	v_mfma_f32_16x16x32_bf16 v[108:111], v[156:159], v[180:183], v[108:111]
	v_mfma_f32_16x16x32_bf16 v[112:115], v[160:163], v[176:179], v[112:115]
	v_mfma_f32_16x16x32_bf16 v[112:115], v[164:167], v[180:183], v[112:115]
	v_mfma_f32_16x16x32_bf16 v[116:119], v[152:155], v[184:187], v[116:119]
	v_mfma_f32_16x16x32_bf16 v[116:119], v[156:159], v[188:191], v[116:119]
	v_mfma_f32_16x16x32_bf16 v[120:123], v[160:163], v[184:187], v[120:123]
	v_mfma_f32_16x16x32_bf16 v[120:123], v[164:167], v[188:191], v[120:123]
	v_mfma_f32_16x16x32_bf16 v[124:127], v[152:155], v[202:205], v[124:127]
	v_mfma_f32_16x16x32_bf16 v[124:127], v[156:159], v[206:209], v[124:127]
	v_mfma_f32_16x16x32_bf16 v[128:131], v[160:163], v[202:205], v[128:131]
	v_mfma_f32_16x16x32_bf16 v[128:131], v[164:167], v[206:209], v[128:131]
	s_setprio 0
	s_barrier
	s_add_i32 s8, s72, 2
	s_add_u32 s52, s52, 0x100
	s_addc_u32 s53, s53, 0
	s_add_u32 s26, s26, 0x100
	s_addc_u32 s27, s27, 0
	s_cmp_ge_i32 s72, s82
	s_mov_b32 s72, s8
	s_cbranch_scc0 .LBB0_287

.LBB0_429:
	ds_read_b128 v[136:139], v2
	ds_read_b128 v[140:143], v2 offset:1024
	ds_read_b128 v[144:147], v2 offset:2048
	ds_read_b128 v[148:151], v2 offset:3072
	ds_read_b128 v[152:155], v132
	ds_read_b128 v[156:159], v132 offset:1024
	ds_read_b128 v[160:163], v132 offset:2048
	ds_read_b128 v[164:167], v132 offset:3072
	s_cmp_eq_u32 s73, s66
	s_cselect_b32 s17, s51, s49
	s_cselect_b32 s16, s50, s48
	s_cselect_b32 s21, s15, s27
	s_cselect_b32 s20, s14, s26
	s_add_u32 s18, s26, 0xffffff80
	s_addc_u32 s19, s27, -1
	s_mov_b32 m0, s40
	s_mov_b64 s[96:97], s[18:19]
	ds_read_b128 v[168:171], v199
	ds_read_b128 v[172:175], v199 offset:1024
	ds_read_b128 v[176:179], v199 offset:2048
	ds_read_b128 v[180:183], v199 offset:3072
	ds_read_b128 v[184:187], v199 offset:4096
	ds_read_b128 v[188:191], v199 offset:5120
	ds_read_b128 v[202:205], v199 offset:6144
	ds_read_b128 v[206:209], v199 offset:7168
	s_add_u32 s18, s18, s52
	global_load_lds_dwordx4 v194, s[96:97]
	s_mov_b32 m0, s41
	s_addc_u32 s19, s19, s53
	global_load_lds_dwordx4 v195, s[96:97]
	s_mov_b32 m0, s42
	s_nop 0
	global_load_lds_dwordx4 v194, s[18:19]
	s_mov_b64 s[100:101], s[18:19]
	s_waitcnt vmcnt(7)
	s_waitcnt lgkmcnt(0)
	s_add_u32 s18, s16, 0x80
	s_addc_u32 s19, s17, 0
	s_barrier
	s_setprio 1
	s_waitcnt lgkmcnt(0)
	v_mfma_f32_16x16x32_bf16 v[4:7], v[136:139], v[168:171], v[4:7]
	v_mfma_f32_16x16x32_bf16 v[4:7], v[140:143], v[172:175], v[4:7]
	v_mfma_f32_16x16x32_bf16 v[8:11], v[144:147], v[168:171], v[8:11]
	v_mfma_f32_16x16x32_bf16 v[8:11], v[148:151], v[172:175], v[8:11]
	v_mfma_f32_16x16x32_bf16 v[12:15], v[136:139], v[176:179], v[12:15]
	v_mfma_f32_16x16x32_bf16 v[12:15], v[140:143], v[180:183], v[12:15]
	v_mfma_f32_16x16x32_bf16 v[16:19], v[144:147], v[176:179], v[16:19]
	v_mfma_f32_16x16x32_bf16 v[16:19], v[148:151], v[180:183], v[16:19]
	v_mfma_f32_16x16x32_bf16 v[20:23], v[136:139], v[184:187], v[20:23]
	v_mfma_f32_16x16x32_bf16 v[20:23], v[140:143], v[188:191], v[20:23]
	v_mfma_f32_16x16x32_bf16 v[24:27], v[144:147], v[184:187], v[24:27]
	v_mfma_f32_16x16x32_bf16 v[24:27], v[148:151], v[188:191], v[24:27]
	v_mfma_f32_16x16x32_bf16 v[28:31], v[136:139], v[202:205], v[28:31]
	v_mfma_f32_16x16x32_bf16 v[28:31], v[140:143], v[206:209], v[28:31]
	v_mfma_f32_16x16x32_bf16 v[32:35], v[144:147], v[202:205], v[32:35]
	v_mfma_f32_16x16x32_bf16 v[32:35], v[148:151], v[206:209], v[32:35]
	s_setprio 0
	s_setprio 1
	v_mfma_f32_16x16x32_bf16 v[36:39], v[152:155], v[168:171], v[36:39]
	v_mfma_f32_16x16x32_bf16 v[36:39], v[156:159], v[172:175], v[36:39]
	v_mfma_f32_16x16x32_bf16 v[40:43], v[160:163], v[168:171], v[40:43]
	v_mfma_f32_16x16x32_bf16 v[40:43], v[164:167], v[172:175], v[40:43]
	v_mfma_f32_16x16x32_bf16 v[44:47], v[152:155], v[176:179], v[44:47]
	v_mfma_f32_16x16x32_bf16 v[44:47], v[156:159], v[180:183], v[44:47]
	v_mfma_f32_16x16x32_bf16 v[48:51], v[160:163], v[176:179], v[48:51]
	v_mfma_f32_16x16x32_bf16 v[48:51], v[164:167], v[180:183], v[48:51]
	v_mfma_f32_16x16x32_bf16 v[52:55], v[152:155], v[184:187], v[52:55]
	v_mfma_f32_16x16x32_bf16 v[52:55], v[156:159], v[188:191], v[52:55]
	v_mfma_f32_16x16x32_bf16 v[56:59], v[160:163], v[184:187], v[56:59]
	v_mfma_f32_16x16x32_bf16 v[56:59], v[164:167], v[188:191], v[56:59]
	v_mfma_f32_16x16x32_bf16 v[60:63], v[152:155], v[202:205], v[60:63]
	v_mfma_f32_16x16x32_bf16 v[60:63], v[156:159], v[206:209], v[60:63]
	v_mfma_f32_16x16x32_bf16 v[64:67], v[160:163], v[202:205], v[64:67]
	v_mfma_f32_16x16x32_bf16 v[64:67], v[164:167], v[206:209], v[64:67]
	s_setprio 0
	s_barrier
	s_mov_b32 m0, s43
	s_nop 0
	global_load_lds_dwordx4 v195, s[100:101]
	s_mov_b32 m0, s44
	s_mov_b64 s[96:97], s[16:17]
	ds_read_b128 v[168:171], v199 offset:16384
	ds_read_b128 v[172:175], v199 offset:17408
	ds_read_b128 v[176:179], v199 offset:18432
	ds_read_b128 v[180:183], v199 offset:19456
	ds_read_b128 v[184:187], v199 offset:20480
	ds_read_b128 v[188:191], v199 offset:21504
	ds_read_b128 v[202:205], v199 offset:22528
	ds_read_b128 v[206:209], v199 offset:23552
	s_add_u32 s16, s16, s52
	global_load_lds_dwordx4 v201, s[96:97]
	s_mov_b32 m0, s45
	s_addc_u32 s17, s17, s53
	global_load_lds_dwordx4 v200, s[96:97]
	s_mov_b32 m0, s30
	s_nop 0
	global_load_lds_dwordx4 v201, s[16:17]
	s_mov_b32 m0, s31
	s_nop 0
	global_load_lds_dwordx4 v200, s[16:17]
	s_waitcnt vmcnt(6)
	s_waitcnt lgkmcnt(0)
	s_barrier
	s_setprio 1
	s_waitcnt lgkmcnt(0)
	v_mfma_f32_16x16x32_bf16 v[68:71], v[136:139], v[168:171], v[68:71]
	v_mfma_f32_16x16x32_bf16 v[68:71], v[140:143], v[172:175], v[68:71]
	v_mfma_f32_16x16x32_bf16 v[72:75], v[144:147], v[168:171], v[72:75]
	v_mfma_f32_16x16x32_bf16 v[72:75], v[148:151], v[172:175], v[72:75]
	v_mfma_f32_16x16x32_bf16 v[76:79], v[136:139], v[176:179], v[76:79]
	v_mfma_f32_16x16x32_bf16 v[76:79], v[140:143], v[180:183], v[76:79]
	v_mfma_f32_16x16x32_bf16 v[80:83], v[144:147], v[176:179], v[80:83]
	v_mfma_f32_16x16x32_bf16 v[80:83], v[148:151], v[180:183], v[80:83]
	v_mfma_f32_16x16x32_bf16 v[84:87], v[136:139], v[184:187], v[84:87]
	v_mfma_f32_16x16x32_bf16 v[84:87], v[140:143], v[188:191], v[84:87]
	v_mfma_f32_16x16x32_bf16 v[88:91], v[144:147], v[184:187], v[88:91]
	v_mfma_f32_16x16x32_bf16 v[88:91], v[148:151], v[188:191], v[88:91]
	v_mfma_f32_16x16x32_bf16 v[92:95], v[136:139], v[202:205], v[92:95]
	v_mfma_f32_16x16x32_bf16 v[92:95], v[140:143], v[206:209], v[92:95]
	v_mfma_f32_16x16x32_bf16 v[96:99], v[144:147], v[202:205], v[96:99]
	v_mfma_f32_16x16x32_bf16 v[96:99], v[148:151], v[206:209], v[96:99]
	s_setprio 0
	s_setprio 1
	v_mfma_f32_16x16x32_bf16 v[100:103], v[152:155], v[168:171], v[100:103]
	v_mfma_f32_16x16x32_bf16 v[100:103], v[156:159], v[172:175], v[100:103]
	v_mfma_f32_16x16x32_bf16 v[104:107], v[160:163], v[168:171], v[104:107]
	v_mfma_f32_16x16x32_bf16 v[104:107], v[164:167], v[172:175], v[104:107]
	v_mfma_f32_16x16x32_bf16 v[108:111], v[152:155], v[176:179], v[108:111]
	v_mfma_f32_16x16x32_bf16 v[108:111], v[156:159], v[180:183], v[108:111]
	v_mfma_f32_16x16x32_bf16 v[112:115], v[160:163], v[176:179], v[112:115]
	v_mfma_f32_16x16x32_bf16 v[112:115], v[164:167], v[180:183], v[112:115]
	v_mfma_f32_16x16x32_bf16 v[116:119], v[152:155], v[184:187], v[116:119]
	v_mfma_f32_16x16x32_bf16 v[116:119], v[156:159], v[188:191], v[116:119]
	v_mfma_f32_16x16x32_bf16 v[120:123], v[160:163], v[184:187], v[120:123]
	v_mfma_f32_16x16x32_bf16 v[120:123], v[164:167], v[188:191], v[120:123]
	v_mfma_f32_16x16x32_bf16 v[124:127], v[152:155], v[202:205], v[124:127]
	v_mfma_f32_16x16x32_bf16 v[124:127], v[156:159], v[206:209], v[124:127]
	v_mfma_f32_16x16x32_bf16 v[128:131], v[160:163], v[202:205], v[128:131]
	v_mfma_f32_16x16x32_bf16 v[128:131], v[164:167], v[206:209], v[128:131]
	s_setprio 0
	s_barrier
	ds_read_b128 v[136:139], v133
	ds_read_b128 v[140:143], v133 offset:1024
	ds_read_b128 v[144:147], v133 offset:2048
	ds_read_b128 v[148:151], v133 offset:3072
	ds_read_b128 v[152:155], v134
	ds_read_b128 v[156:159], v134 offset:1024
	ds_read_b128 v[160:163], v134 offset:2048
	ds_read_b128 v[164:167], v134 offset:3072
	s_mov_b32 m0, s84
	s_mov_b64 s[16:17], s[20:21]
	ds_read_b128 v[168:171], v199 offset:32768
	ds_read_b128 v[172:175], v199 offset:33792
	ds_read_b128 v[176:179], v199 offset:34816
	ds_read_b128 v[180:183], v199 offset:35840
	ds_read_b128 v[184:187], v199 offset:36864
	ds_read_b128 v[188:191], v199 offset:37888
	ds_read_b128 v[202:205], v199 offset:38912
	ds_read_b128 v[206:209], v199 offset:39936
	s_nop 0
	global_load_lds_dwordx4 v194, s[16:17]
	s_mov_b32 m0, s85
	s_nop 0
	global_load_lds_dwordx4 v195, s[16:17]
	s_add_u32 s16, s20, s52
	s_addc_u32 s17, s21, s53
	s_mov_b32 m0, s86
	s_nop 0
	global_load_lds_dwordx4 v194, s[16:17]
	s_mov_b64 s[100:101], s[16:17]
	s_waitcnt vmcnt(7)
	s_waitcnt lgkmcnt(0)
	s_barrier
	s_setprio 1
	s_waitcnt lgkmcnt(0)
	v_mfma_f32_16x16x32_bf16 v[4:7], v[136:139], v[168:171], v[4:7]
	v_mfma_f32_16x16x32_bf16 v[4:7], v[140:143], v[172:175], v[4:7]
	v_mfma_f32_16x16x32_bf16 v[8:11], v[144:147], v[168:171], v[8:11]
	v_mfma_f32_16x16x32_bf16 v[8:11], v[148:151], v[172:175], v[8:11]
	v_mfma_f32_16x16x32_bf16 v[12:15], v[136:139], v[176:179], v[12:15]
	v_mfma_f32_16x16x32_bf16 v[12:15], v[140:143], v[180:183], v[12:15]
	v_mfma_f32_16x16x32_bf16 v[16:19], v[144:147], v[176:179], v[16:19]
	v_mfma_f32_16x16x32_bf16 v[16:19], v[148:151], v[180:183], v[16:19]
	v_mfma_f32_16x16x32_bf16 v[20:23], v[136:139], v[184:187], v[20:23]
	v_mfma_f32_16x16x32_bf16 v[20:23], v[140:143], v[188:191], v[20:23]
	v_mfma_f32_16x16x32_bf16 v[24:27], v[144:147], v[184:187], v[24:27]
	v_mfma_f32_16x16x32_bf16 v[24:27], v[148:151], v[188:191], v[24:27]
	v_mfma_f32_16x16x32_bf16 v[28:31], v[136:139], v[202:205], v[28:31]
	v_mfma_f32_16x16x32_bf16 v[28:31], v[140:143], v[206:209], v[28:31]
	v_mfma_f32_16x16x32_bf16 v[32:35], v[144:147], v[202:205], v[32:35]
	v_mfma_f32_16x16x32_bf16 v[32:35], v[148:151], v[206:209], v[32:35]
	s_setprio 0
	s_setprio 1
	v_mfma_f32_16x16x32_bf16 v[36:39], v[152:155], v[168:171], v[36:39]
	v_mfma_f32_16x16x32_bf16 v[36:39], v[156:159], v[172:175], v[36:39]
	v_mfma_f32_16x16x32_bf16 v[40:43], v[160:163], v[168:171], v[40:43]
	v_mfma_f32_16x16x32_bf16 v[40:43], v[164:167], v[172:175], v[40:43]
	v_mfma_f32_16x16x32_bf16 v[44:47], v[152:155], v[176:179], v[44:47]
	v_mfma_f32_16x16x32_bf16 v[44:47], v[156:159], v[180:183], v[44:47]
	v_mfma_f32_16x16x32_bf16 v[48:51], v[160:163], v[176:179], v[48:51]
	v_mfma_f32_16x16x32_bf16 v[48:51], v[164:167], v[180:183], v[48:51]
	v_mfma_f32_16x16x32_bf16 v[52:55], v[152:155], v[184:187], v[52:55]
	v_mfma_f32_16x16x32_bf16 v[52:55], v[156:159], v[188:191], v[52:55]
	v_mfma_f32_16x16x32_bf16 v[56:59], v[160:163], v[184:187], v[56:59]
	v_mfma_f32_16x16x32_bf16 v[56:59], v[164:167], v[188:191], v[56:59]
	v_mfma_f32_16x16x32_bf16 v[60:63], v[152:155], v[202:205], v[60:63]
	v_mfma_f32_16x16x32_bf16 v[60:63], v[156:159], v[206:209], v[60:63]
	v_mfma_f32_16x16x32_bf16 v[64:67], v[160:163], v[202:205], v[64:67]
	v_mfma_f32_16x16x32_bf16 v[64:67], v[164:167], v[206:209], v[64:67]
	s_setprio 0
	s_barrier
	s_mov_b32 m0, s87
	s_nop 0
	global_load_lds_dwordx4 v195, s[100:101]
	s_mov_b32 m0, s46
	s_mov_b64 s[16:17], s[18:19]
	ds_read_b128 v[168:171], v199 offset:49152
	ds_read_b128 v[172:175], v199 offset:50176
	ds_read_b128 v[176:179], v199 offset:51200
	ds_read_b128 v[180:183], v199 offset:52224
	ds_read_b128 v[184:187], v199 offset:53248
	ds_read_b128 v[188:191], v199 offset:54272
	ds_read_b128 v[202:205], v199 offset:55296
	ds_read_b128 v[206:209], v199 offset:56320
	s_nop 0
	global_load_lds_dwordx4 v201, s[16:17]
	s_mov_b32 m0, s47
	s_nop 0
	global_load_lds_dwordx4 v200, s[16:17]
	s_add_u32 s16, s18, s52
	s_addc_u32 s17, s19, s53
	s_mov_b32 m0, s28
	s_nop 0
	global_load_lds_dwordx4 v201, s[16:17]
	s_mov_b32 m0, s29
	s_nop 0
	global_load_lds_dwordx4 v200, s[16:17]
	s_waitcnt vmcnt(6)
	s_waitcnt lgkmcnt(0)
	s_barrier
	s_setprio 1
	s_waitcnt lgkmcnt(0)
	v_mfma_f32_16x16x32_bf16 v[68:71], v[136:139], v[168:171], v[68:71]
	v_mfma_f32_16x16x32_bf16 v[68:71], v[140:143], v[172:175], v[68:71]
	v_mfma_f32_16x16x32_bf16 v[72:75], v[144:147], v[168:171], v[72:75]
	v_mfma_f32_16x16x32_bf16 v[72:75], v[148:151], v[172:175], v[72:75]
	v_mfma_f32_16x16x32_bf16 v[76:79], v[136:139], v[176:179], v[76:79]
	v_mfma_f32_16x16x32_bf16 v[76:79], v[140:143], v[180:183], v[76:79]
	v_mfma_f32_16x16x32_bf16 v[80:83], v[144:147], v[176:179], v[80:83]
	v_mfma_f32_16x16x32_bf16 v[80:83], v[148:151], v[180:183], v[80:83]
	v_mfma_f32_16x16x32_bf16 v[84:87], v[136:139], v[184:187], v[84:87]
	v_mfma_f32_16x16x32_bf16 v[84:87], v[140:143], v[188:191], v[84:87]
	v_mfma_f32_16x16x32_bf16 v[88:91], v[144:147], v[184:187], v[88:91]
	v_mfma_f32_16x16x32_bf16 v[88:91], v[148:151], v[188:191], v[88:91]
	v_mfma_f32_16x16x32_bf16 v[92:95], v[136:139], v[202:205], v[92:95]
	v_mfma_f32_16x16x32_bf16 v[92:95], v[140:143], v[206:209], v[92:95]
	v_mfma_f32_16x16x32_bf16 v[96:99], v[144:147], v[202:205], v[96:99]
	v_mfma_f32_16x16x32_bf16 v[96:99], v[148:151], v[206:209], v[96:99]
	s_setprio 0
	s_setprio 1
	v_mfma_f32_16x16x32_bf16 v[100:103], v[152:155], v[168:171], v[100:103]
	v_mfma_f32_16x16x32_bf16 v[100:103], v[156:159], v[172:175], v[100:103]
	v_mfma_f32_16x16x32_bf16 v[104:107], v[160:163], v[168:171], v[104:107]
	v_mfma_f32_16x16x32_bf16 v[104:107], v[164:167], v[172:175], v[104:107]
	v_mfma_f32_16x16x32_bf16 v[108:111], v[152:155], v[176:179], v[108:111]
	v_mfma_f32_16x16x32_bf16 v[108:111], v[156:159], v[180:183], v[108:111]
	v_mfma_f32_16x16x32_bf16 v[112:115], v[160:163], v[176:179], v[112:115]
	v_mfma_f32_16x16x32_bf16 v[112:115], v[164:167], v[180:183], v[112:115]
	v_mfma_f32_16x16x32_bf16 v[116:119], v[152:155], v[184:187], v[116:119]
	v_mfma_f32_16x16x32_bf16 v[116:119], v[156:159], v[188:191], v[116:119]
	v_mfma_f32_16x16x32_bf16 v[120:123], v[160:163], v[184:187], v[120:123]
	v_mfma_f32_16x16x32_bf16 v[120:123], v[164:167], v[188:191], v[120:123]
	v_mfma_f32_16x16x32_bf16 v[124:127], v[152:155], v[202:205], v[124:127]
	v_mfma_f32_16x16x32_bf16 v[124:127], v[156:159], v[206:209], v[124:127]
	v_mfma_f32_16x16x32_bf16 v[128:131], v[160:163], v[202:205], v[128:131]
	v_mfma_f32_16x16x32_bf16 v[128:131], v[164:167], v[206:209], v[128:131]
	s_setprio 0
	s_barrier
	s_add_i32 s8, s66, 2
	s_add_u32 s48, s48, 0x100
	s_addc_u32 s49, s49, 0
	s_add_u32 s26, s26, 0x100
	s_addc_u32 s27, s27, 0
	s_cmp_ge_i32 s66, s73
	s_mov_b32 s66, s8
	s_cbranch_scc0 .LBB0_429
	v_readlane_b32 s96, v255, 41
	v_readlane_b32 s97, v255, 42

.LBB0_855:
	ds_read_b128 v[136:139], v132
	ds_read_b128 v[140:143], v132 offset:1024
	ds_read_b128 v[144:147], v132 offset:2048
	ds_read_b128 v[148:151], v132 offset:3072
	ds_read_b128 v[152:155], v133
	ds_read_b128 v[156:159], v133 offset:1024
	ds_read_b128 v[160:163], v133 offset:2048
	ds_read_b128 v[164:167], v133 offset:3072
	s_cmp_eq_u32 s4, s90
	s_cselect_b32 s17, s41, s89
	s_cselect_b32 s16, s40, s88
	s_cselect_b32 s21, s59, s27
	s_cselect_b32 s20, s58, s26
	s_add_u32 s8, s26, 0xffffff80
	s_addc_u32 s9, s27, -1
	s_mov_b32 m0, s80
	s_mov_b64 s[18:19], s[8:9]
	ds_read_b128 v[168:171], v246 offset:8192
	ds_read_b128 v[172:175], v246 offset:9216
	ds_read_b128 v[176:179], v246 offset:10240
	ds_read_b128 v[180:183], v246 offset:11264
	ds_read_b128 v[184:187], v246 offset:12288
	ds_read_b128 v[188:191], v246 offset:13312
	ds_read_b128 v[192:195], v246 offset:14336
	ds_read_b128 v[196:199], v246 offset:15360
	s_add_u32 s8, s8, s42
	global_load_lds_dwordx4 v242, s[18:19]
	s_mov_b32 m0, s81
	s_addc_u32 s9, s9, s43
	global_load_lds_dwordx4 v2, s[18:19]
	s_mov_b32 m0, s82
	s_add_u32 s18, s16, 0x80
	global_load_lds_dwordx4 v242, s[8:9]
	s_addc_u32 s19, s17, 0
	s_mov_b64 s[100:101], s[8:9]
	s_waitcnt vmcnt(7)
	s_waitcnt lgkmcnt(0)
	s_barrier
	s_setprio 1
	s_waitcnt lgkmcnt(0)
	v_mfma_f32_16x16x32_bf16 v[4:7], v[136:139], v[168:171], v[4:7]
	v_mfma_f32_16x16x32_bf16 v[4:7], v[140:143], v[172:175], v[4:7]
	v_mfma_f32_16x16x32_bf16 v[8:11], v[144:147], v[168:171], v[8:11]
	v_mfma_f32_16x16x32_bf16 v[8:11], v[148:151], v[172:175], v[8:11]
	v_mfma_f32_16x16x32_bf16 v[12:15], v[136:139], v[176:179], v[12:15]
	v_mfma_f32_16x16x32_bf16 v[12:15], v[140:143], v[180:183], v[12:15]
	v_mfma_f32_16x16x32_bf16 v[16:19], v[144:147], v[176:179], v[16:19]
	v_mfma_f32_16x16x32_bf16 v[16:19], v[148:151], v[180:183], v[16:19]
	v_mfma_f32_16x16x32_bf16 v[20:23], v[136:139], v[184:187], v[20:23]
	v_mfma_f32_16x16x32_bf16 v[20:23], v[140:143], v[188:191], v[20:23]
	v_mfma_f32_16x16x32_bf16 v[24:27], v[144:147], v[184:187], v[24:27]
	v_mfma_f32_16x16x32_bf16 v[24:27], v[148:151], v[188:191], v[24:27]
	v_mfma_f32_16x16x32_bf16 v[28:31], v[136:139], v[192:195], v[28:31]
	v_mfma_f32_16x16x32_bf16 v[28:31], v[140:143], v[196:199], v[28:31]
	v_mfma_f32_16x16x32_bf16 v[32:35], v[144:147], v[192:195], v[32:35]
	v_mfma_f32_16x16x32_bf16 v[32:35], v[148:151], v[196:199], v[32:35]
	s_setprio 0
	s_setprio 1
	v_mfma_f32_16x16x32_bf16 v[36:39], v[152:155], v[168:171], v[36:39]
	v_mfma_f32_16x16x32_bf16 v[36:39], v[156:159], v[172:175], v[36:39]
	v_mfma_f32_16x16x32_bf16 v[40:43], v[160:163], v[168:171], v[40:43]
	v_mfma_f32_16x16x32_bf16 v[40:43], v[164:167], v[172:175], v[40:43]
	v_mfma_f32_16x16x32_bf16 v[44:47], v[152:155], v[176:179], v[44:47]
	v_mfma_f32_16x16x32_bf16 v[44:47], v[156:159], v[180:183], v[44:47]
	v_mfma_f32_16x16x32_bf16 v[48:51], v[160:163], v[176:179], v[48:51]
	v_mfma_f32_16x16x32_bf16 v[48:51], v[164:167], v[180:183], v[48:51]
	v_mfma_f32_16x16x32_bf16 v[52:55], v[152:155], v[184:187], v[52:55]
	v_mfma_f32_16x16x32_bf16 v[52:55], v[156:159], v[188:191], v[52:55]
	v_mfma_f32_16x16x32_bf16 v[56:59], v[160:163], v[184:187], v[56:59]
	v_mfma_f32_16x16x32_bf16 v[56:59], v[164:167], v[188:191], v[56:59]
	v_mfma_f32_16x16x32_bf16 v[60:63], v[152:155], v[192:195], v[60:63]
	v_mfma_f32_16x16x32_bf16 v[60:63], v[156:159], v[196:199], v[60:63]
	v_mfma_f32_16x16x32_bf16 v[64:67], v[160:163], v[192:195], v[64:67]
	v_mfma_f32_16x16x32_bf16 v[64:67], v[164:167], v[196:199], v[64:67]
	s_setprio 0
	s_barrier
	s_mov_b32 m0, s83
	s_nop 0
	global_load_lds_dwordx4 v2, s[100:101]
	s_mov_b32 m0, s84
	s_mov_b64 s[8:9], s[16:17]
	ds_read_b128 v[168:171], v246 offset:24576
	ds_read_b128 v[172:175], v246 offset:25600
	ds_read_b128 v[176:179], v246 offset:26624
	ds_read_b128 v[180:183], v246 offset:27648
	ds_read_b128 v[184:187], v246 offset:28672
	ds_read_b128 v[188:191], v246 offset:29696
	ds_read_b128 v[192:195], v246 offset:30720
	ds_read_b128 v[196:199], v246 offset:31744
	s_nop 0
	global_load_lds_dwordx4 v248, s[8:9]
	s_mov_b32 m0, s85
	s_nop 0
	global_load_lds_dwordx4 v247, s[8:9]
	s_add_u32 s8, s16, s42
	s_addc_u32 s9, s17, s43
	s_mov_b32 m0, s30
	s_nop 0
	global_load_lds_dwordx4 v248, s[8:9]
	s_mov_b32 m0, s31
	s_nop 0
	global_load_lds_dwordx4 v247, s[8:9]
	s_waitcnt vmcnt(6)
	s_waitcnt lgkmcnt(0)
	s_barrier
	s_setprio 1
	s_waitcnt lgkmcnt(0)
	v_mfma_f32_16x16x32_bf16 v[68:71], v[136:139], v[168:171], v[68:71]
	v_mfma_f32_16x16x32_bf16 v[68:71], v[140:143], v[172:175], v[68:71]
	v_mfma_f32_16x16x32_bf16 v[72:75], v[144:147], v[168:171], v[72:75]
	v_mfma_f32_16x16x32_bf16 v[72:75], v[148:151], v[172:175], v[72:75]
	v_mfma_f32_16x16x32_bf16 v[76:79], v[136:139], v[176:179], v[76:79]
	v_mfma_f32_16x16x32_bf16 v[76:79], v[140:143], v[180:183], v[76:79]
	v_mfma_f32_16x16x32_bf16 v[80:83], v[144:147], v[176:179], v[80:83]
	v_mfma_f32_16x16x32_bf16 v[80:83], v[148:151], v[180:183], v[80:83]
	v_mfma_f32_16x16x32_bf16 v[84:87], v[136:139], v[184:187], v[84:87]
	v_mfma_f32_16x16x32_bf16 v[84:87], v[140:143], v[188:191], v[84:87]
	v_mfma_f32_16x16x32_bf16 v[88:91], v[144:147], v[184:187], v[88:91]
	v_mfma_f32_16x16x32_bf16 v[88:91], v[148:151], v[188:191], v[88:91]
	v_mfma_f32_16x16x32_bf16 v[92:95], v[136:139], v[192:195], v[92:95]
	v_mfma_f32_16x16x32_bf16 v[92:95], v[140:143], v[196:199], v[92:95]
	v_mfma_f32_16x16x32_bf16 v[96:99], v[144:147], v[192:195], v[96:99]
	v_mfma_f32_16x16x32_bf16 v[96:99], v[148:151], v[196:199], v[96:99]
	s_setprio 0
	s_setprio 1
	v_mfma_f32_16x16x32_bf16 v[100:103], v[152:155], v[168:171], v[100:103]
	v_mfma_f32_16x16x32_bf16 v[100:103], v[156:159], v[172:175], v[100:103]
	v_mfma_f32_16x16x32_bf16 v[104:107], v[160:163], v[168:171], v[104:107]
	v_mfma_f32_16x16x32_bf16 v[104:107], v[164:167], v[172:175], v[104:107]
	v_mfma_f32_16x16x32_bf16 v[108:111], v[152:155], v[176:179], v[108:111]
	v_mfma_f32_16x16x32_bf16 v[108:111], v[156:159], v[180:183], v[108:111]
	v_mfma_f32_16x16x32_bf16 v[112:115], v[160:163], v[176:179], v[112:115]
	v_mfma_f32_16x16x32_bf16 v[112:115], v[164:167], v[180:183], v[112:115]
	v_mfma_f32_16x16x32_bf16 v[116:119], v[152:155], v[184:187], v[116:119]
	v_mfma_f32_16x16x32_bf16 v[116:119], v[156:159], v[188:191], v[116:119]
	v_mfma_f32_16x16x32_bf16 v[120:123], v[160:163], v[184:187], v[120:123]
	v_mfma_f32_16x16x32_bf16 v[120:123], v[164:167], v[188:191], v[120:123]
	v_mfma_f32_16x16x32_bf16 v[124:127], v[152:155], v[192:195], v[124:127]
	v_mfma_f32_16x16x32_bf16 v[124:127], v[156:159], v[196:199], v[124:127]
	v_mfma_f32_16x16x32_bf16 v[128:131], v[160:163], v[192:195], v[128:131]
	v_mfma_f32_16x16x32_bf16 v[128:131], v[164:167], v[196:199], v[128:131]
	s_setprio 0
	s_barrier
	ds_read_b128 v[136:139], v134
	ds_read_b128 v[140:143], v134 offset:1024
	ds_read_b128 v[144:147], v134 offset:2048
	ds_read_b128 v[148:151], v134 offset:3072
	ds_read_b128 v[152:155], v135
	ds_read_b128 v[156:159], v135 offset:1024
	ds_read_b128 v[160:163], v135 offset:2048
	ds_read_b128 v[164:167], v135 offset:3072
	s_mov_b32 m0, s7
	s_mov_b64 s[8:9], s[20:21]
	ds_read_b128 v[168:171], v246 offset:40960
	ds_read_b128 v[172:175], v246 offset:41984
	ds_read_b128 v[176:179], v246 offset:43008
	ds_read_b128 v[180:183], v246 offset:44032
	ds_read_b128 v[184:187], v246 offset:45056
	ds_read_b128 v[188:191], v246 offset:46080
	ds_read_b128 v[192:195], v246 offset:47104
	ds_read_b128 v[196:199], v246 offset:48128
	s_nop 0
	global_load_lds_dwordx4 v242, s[8:9]
	s_mov_b32 m0, s69
	s_nop 0
	global_load_lds_dwordx4 v2, s[8:9]
	s_add_u32 s8, s20, s42
	s_addc_u32 s9, s21, s43
	s_mov_b32 m0, s72
	s_nop 0
	global_load_lds_dwordx4 v242, s[8:9]
	s_mov_b64 s[100:101], s[8:9]
	s_waitcnt vmcnt(7)
	s_waitcnt lgkmcnt(0)
	s_barrier
	s_setprio 1
	s_waitcnt lgkmcnt(0)
	v_mfma_f32_16x16x32_bf16 v[4:7], v[136:139], v[168:171], v[4:7]
	v_mfma_f32_16x16x32_bf16 v[4:7], v[140:143], v[172:175], v[4:7]
	v_mfma_f32_16x16x32_bf16 v[8:11], v[144:147], v[168:171], v[8:11]
	v_mfma_f32_16x16x32_bf16 v[8:11], v[148:151], v[172:175], v[8:11]
	v_mfma_f32_16x16x32_bf16 v[12:15], v[136:139], v[176:179], v[12:15]
	v_mfma_f32_16x16x32_bf16 v[12:15], v[140:143], v[180:183], v[12:15]
	v_mfma_f32_16x16x32_bf16 v[16:19], v[144:147], v[176:179], v[16:19]
	v_mfma_f32_16x16x32_bf16 v[16:19], v[148:151], v[180:183], v[16:19]
	v_mfma_f32_16x16x32_bf16 v[20:23], v[136:139], v[184:187], v[20:23]
	v_mfma_f32_16x16x32_bf16 v[20:23], v[140:143], v[188:191], v[20:23]
	v_mfma_f32_16x16x32_bf16 v[24:27], v[144:147], v[184:187], v[24:27]
	v_mfma_f32_16x16x32_bf16 v[24:27], v[148:151], v[188:191], v[24:27]
	v_mfma_f32_16x16x32_bf16 v[28:31], v[136:139], v[192:195], v[28:31]
	v_mfma_f32_16x16x32_bf16 v[28:31], v[140:143], v[196:199], v[28:31]
	v_mfma_f32_16x16x32_bf16 v[32:35], v[144:147], v[192:195], v[32:35]
	v_mfma_f32_16x16x32_bf16 v[32:35], v[148:151], v[196:199], v[32:35]
	s_setprio 0
	s_setprio 1
	v_mfma_f32_16x16x32_bf16 v[36:39], v[152:155], v[168:171], v[36:39]
	v_mfma_f32_16x16x32_bf16 v[36:39], v[156:159], v[172:175], v[36:39]
	v_mfma_f32_16x16x32_bf16 v[40:43], v[160:163], v[168:171], v[40:43]
	v_mfma_f32_16x16x32_bf16 v[40:43], v[164:167], v[172:175], v[40:43]
	v_mfma_f32_16x16x32_bf16 v[44:47], v[152:155], v[176:179], v[44:47]
	v_mfma_f32_16x16x32_bf16 v[44:47], v[156:159], v[180:183], v[44:47]
	v_mfma_f32_16x16x32_bf16 v[48:51], v[160:163], v[176:179], v[48:51]
	v_mfma_f32_16x16x32_bf16 v[48:51], v[164:167], v[180:183], v[48:51]
	v_mfma_f32_16x16x32_bf16 v[52:55], v[152:155], v[184:187], v[52:55]
	v_mfma_f32_16x16x32_bf16 v[52:55], v[156:159], v[188:191], v[52:55]
	v_mfma_f32_16x16x32_bf16 v[56:59], v[160:163], v[184:187], v[56:59]
	v_mfma_f32_16x16x32_bf16 v[56:59], v[164:167], v[188:191], v[56:59]
	v_mfma_f32_16x16x32_bf16 v[60:63], v[152:155], v[192:195], v[60:63]
	v_mfma_f32_16x16x32_bf16 v[60:63], v[156:159], v[196:199], v[60:63]
	v_mfma_f32_16x16x32_bf16 v[64:67], v[160:163], v[192:195], v[64:67]
	v_mfma_f32_16x16x32_bf16 v[64:67], v[164:167], v[196:199], v[64:67]
	s_setprio 0
	s_barrier
	s_mov_b32 m0, s73
	s_nop 0
	global_load_lds_dwordx4 v2, s[100:101]
	s_mov_b32 m0, s86
	s_mov_b64 s[8:9], s[18:19]
	ds_read_b128 v[168:171], v246 offset:57344
	ds_read_b128 v[172:175], v246 offset:58368
	ds_read_b128 v[176:179], v246 offset:59392
	ds_read_b128 v[180:183], v246 offset:60416
	ds_read_b128 v[184:187], v246 offset:61440
	ds_read_b128 v[188:191], v246 offset:62464
	ds_read_b128 v[192:195], v246 offset:63488
	ds_read_b128 v[196:199], v246 offset:64512
	s_nop 0
	global_load_lds_dwordx4 v248, s[8:9]
	s_mov_b32 m0, s87
	s_nop 0
	global_load_lds_dwordx4 v247, s[8:9]
	s_add_u32 s8, s18, s42
	s_addc_u32 s9, s19, s43
	s_mov_b32 m0, s28
	s_nop 0
	global_load_lds_dwordx4 v248, s[8:9]
	s_mov_b32 m0, s29
	s_nop 0
	global_load_lds_dwordx4 v247, s[8:9]
	s_waitcnt vmcnt(6)
	s_waitcnt lgkmcnt(0)
	s_barrier
	s_setprio 1
	s_waitcnt lgkmcnt(0)
	v_mfma_f32_16x16x32_bf16 v[68:71], v[136:139], v[168:171], v[68:71]
	v_mfma_f32_16x16x32_bf16 v[68:71], v[140:143], v[172:175], v[68:71]
	v_mfma_f32_16x16x32_bf16 v[72:75], v[144:147], v[168:171], v[72:75]
	v_mfma_f32_16x16x32_bf16 v[72:75], v[148:151], v[172:175], v[72:75]
	v_mfma_f32_16x16x32_bf16 v[76:79], v[136:139], v[176:179], v[76:79]
	v_mfma_f32_16x16x32_bf16 v[76:79], v[140:143], v[180:183], v[76:79]
	v_mfma_f32_16x16x32_bf16 v[80:83], v[144:147], v[176:179], v[80:83]
	v_mfma_f32_16x16x32_bf16 v[80:83], v[148:151], v[180:183], v[80:83]
	v_mfma_f32_16x16x32_bf16 v[84:87], v[136:139], v[184:187], v[84:87]
	v_mfma_f32_16x16x32_bf16 v[84:87], v[140:143], v[188:191], v[84:87]
	v_mfma_f32_16x16x32_bf16 v[88:91], v[144:147], v[184:187], v[88:91]
	v_mfma_f32_16x16x32_bf16 v[88:91], v[148:151], v[188:191], v[88:91]
	v_mfma_f32_16x16x32_bf16 v[92:95], v[136:139], v[192:195], v[92:95]
	v_mfma_f32_16x16x32_bf16 v[92:95], v[140:143], v[196:199], v[92:95]
	v_mfma_f32_16x16x32_bf16 v[96:99], v[144:147], v[192:195], v[96:99]
	v_mfma_f32_16x16x32_bf16 v[96:99], v[148:151], v[196:199], v[96:99]
	s_setprio 0
	s_setprio 1
	v_mfma_f32_16x16x32_bf16 v[100:103], v[152:155], v[168:171], v[100:103]
	v_mfma_f32_16x16x32_bf16 v[100:103], v[156:159], v[172:175], v[100:103]
	v_mfma_f32_16x16x32_bf16 v[104:107], v[160:163], v[168:171], v[104:107]
	v_mfma_f32_16x16x32_bf16 v[104:107], v[164:167], v[172:175], v[104:107]
	v_mfma_f32_16x16x32_bf16 v[108:111], v[152:155], v[176:179], v[108:111]
	v_mfma_f32_16x16x32_bf16 v[108:111], v[156:159], v[180:183], v[108:111]
	v_mfma_f32_16x16x32_bf16 v[112:115], v[160:163], v[176:179], v[112:115]
	v_mfma_f32_16x16x32_bf16 v[112:115], v[164:167], v[180:183], v[112:115]
	v_mfma_f32_16x16x32_bf16 v[116:119], v[152:155], v[184:187], v[116:119]
	v_mfma_f32_16x16x32_bf16 v[116:119], v[156:159], v[188:191], v[116:119]
	v_mfma_f32_16x16x32_bf16 v[120:123], v[160:163], v[184:187], v[120:123]
	v_mfma_f32_16x16x32_bf16 v[120:123], v[164:167], v[188:191], v[120:123]
	v_mfma_f32_16x16x32_bf16 v[124:127], v[152:155], v[192:195], v[124:127]
	v_mfma_f32_16x16x32_bf16 v[124:127], v[156:159], v[196:199], v[124:127]
	v_mfma_f32_16x16x32_bf16 v[128:131], v[160:163], v[192:195], v[128:131]
	v_mfma_f32_16x16x32_bf16 v[128:131], v[164:167], v[196:199], v[128:131]
	s_setprio 0
	s_barrier
	s_add_i32 s8, s90, 2
	s_add_u32 s88, s88, 0x100
	s_addc_u32 s89, s89, 0
	s_add_u32 s26, s26, 0x100
	s_addc_u32 s27, s27, 0
	s_cmp_ge_i32 s90, s4
	s_mov_b32 s90, s8
	s_cbranch_scc0 .LBB0_855
	v_readlane_b32 s90, v255, 45
	v_readlane_b32 s91, v255, 46
	s_movk_i32 s89, 0x61

.LBB0_880:
	ds_read_b128 v[136:139], v132
	ds_read_b128 v[140:143], v132 offset:1024
	ds_read_b128 v[144:147], v132 offset:2048
	ds_read_b128 v[148:151], v132 offset:3072
	ds_read_b128 v[152:155], v133
	ds_read_b128 v[156:159], v133 offset:1024
	ds_read_b128 v[160:163], v133 offset:2048
	ds_read_b128 v[164:167], v133 offset:3072
	s_cmp_eq_u32 s4, s88
	s_cselect_b32 s17, s43, s87
	s_cselect_b32 s16, s42, s86
	s_cselect_b32 s21, s41, s27
	s_cselect_b32 s20, s40, s26
	s_add_u32 s8, s26, 0xffffff80
	s_addc_u32 s9, s27, -1
	s_mov_b32 m0, s78
	s_mov_b64 s[18:19], s[8:9]
	ds_read_b128 v[168:171], v246
	ds_read_b128 v[172:175], v246 offset:1024
	ds_read_b128 v[176:179], v246 offset:2048
	ds_read_b128 v[180:183], v246 offset:3072
	ds_read_b128 v[184:187], v246 offset:4096
	ds_read_b128 v[188:191], v246 offset:5120
	ds_read_b128 v[192:195], v246 offset:6144
	ds_read_b128 v[196:199], v246 offset:7168
	s_add_u32 s8, s8, s46
	global_load_lds_dwordx4 v242, s[18:19]
	s_mov_b32 m0, s79
	s_addc_u32 s9, s9, s47
	global_load_lds_dwordx4 v2, s[18:19]
	s_mov_b32 m0, s80
	s_add_u32 s18, s16, 0x80
	global_load_lds_dwordx4 v242, s[8:9]
	s_addc_u32 s19, s17, 0
	s_mov_b64 s[100:101], s[8:9]
	s_waitcnt vmcnt(7)
	s_waitcnt lgkmcnt(0)
	s_barrier
	s_setprio 1
	s_waitcnt lgkmcnt(0)
	v_mfma_f32_16x16x32_bf16 v[4:7], v[136:139], v[168:171], v[4:7]
	v_mfma_f32_16x16x32_bf16 v[4:7], v[140:143], v[172:175], v[4:7]
	v_mfma_f32_16x16x32_bf16 v[8:11], v[144:147], v[168:171], v[8:11]
	v_mfma_f32_16x16x32_bf16 v[8:11], v[148:151], v[172:175], v[8:11]
	v_mfma_f32_16x16x32_bf16 v[12:15], v[136:139], v[176:179], v[12:15]
	v_mfma_f32_16x16x32_bf16 v[12:15], v[140:143], v[180:183], v[12:15]
	v_mfma_f32_16x16x32_bf16 v[16:19], v[144:147], v[176:179], v[16:19]
	v_mfma_f32_16x16x32_bf16 v[16:19], v[148:151], v[180:183], v[16:19]
	v_mfma_f32_16x16x32_bf16 v[20:23], v[136:139], v[184:187], v[20:23]
	v_mfma_f32_16x16x32_bf16 v[20:23], v[140:143], v[188:191], v[20:23]
	v_mfma_f32_16x16x32_bf16 v[24:27], v[144:147], v[184:187], v[24:27]
	v_mfma_f32_16x16x32_bf16 v[24:27], v[148:151], v[188:191], v[24:27]
	v_mfma_f32_16x16x32_bf16 v[28:31], v[136:139], v[192:195], v[28:31]
	v_mfma_f32_16x16x32_bf16 v[28:31], v[140:143], v[196:199], v[28:31]
	v_mfma_f32_16x16x32_bf16 v[32:35], v[144:147], v[192:195], v[32:35]
	v_mfma_f32_16x16x32_bf16 v[32:35], v[148:151], v[196:199], v[32:35]
	s_setprio 0
	s_setprio 1
	v_mfma_f32_16x16x32_bf16 v[36:39], v[152:155], v[168:171], v[36:39]
	v_mfma_f32_16x16x32_bf16 v[36:39], v[156:159], v[172:175], v[36:39]
	v_mfma_f32_16x16x32_bf16 v[40:43], v[160:163], v[168:171], v[40:43]
	v_mfma_f32_16x16x32_bf16 v[40:43], v[164:167], v[172:175], v[40:43]
	v_mfma_f32_16x16x32_bf16 v[44:47], v[152:155], v[176:179], v[44:47]
	v_mfma_f32_16x16x32_bf16 v[44:47], v[156:159], v[180:183], v[44:47]
	v_mfma_f32_16x16x32_bf16 v[48:51], v[160:163], v[176:179], v[48:51]
	v_mfma_f32_16x16x32_bf16 v[48:51], v[164:167], v[180:183], v[48:51]
	v_mfma_f32_16x16x32_bf16 v[52:55], v[152:155], v[184:187], v[52:55]
	v_mfma_f32_16x16x32_bf16 v[52:55], v[156:159], v[188:191], v[52:55]
	v_mfma_f32_16x16x32_bf16 v[56:59], v[160:163], v[184:187], v[56:59]
	v_mfma_f32_16x16x32_bf16 v[56:59], v[164:167], v[188:191], v[56:59]
	v_mfma_f32_16x16x32_bf16 v[60:63], v[152:155], v[192:195], v[60:63]
	v_mfma_f32_16x16x32_bf16 v[60:63], v[156:159], v[196:199], v[60:63]
	v_mfma_f32_16x16x32_bf16 v[64:67], v[160:163], v[192:195], v[64:67]
	v_mfma_f32_16x16x32_bf16 v[64:67], v[164:167], v[196:199], v[64:67]
	s_setprio 0
	s_barrier
	s_mov_b32 m0, s81
	s_nop 0
	global_load_lds_dwordx4 v2, s[100:101]
	s_mov_b32 m0, s82
	s_mov_b64 s[8:9], s[16:17]
	ds_read_b128 v[168:171], v246 offset:16384
	ds_read_b128 v[172:175], v246 offset:17408
	ds_read_b128 v[176:179], v246 offset:18432
	ds_read_b128 v[180:183], v246 offset:19456
	ds_read_b128 v[184:187], v246 offset:20480
	ds_read_b128 v[188:191], v246 offset:21504
	ds_read_b128 v[192:195], v246 offset:22528
	ds_read_b128 v[196:199], v246 offset:23552
	s_nop 0
	global_load_lds_dwordx4 v248, s[8:9]
	s_mov_b32 m0, s83
	s_nop 0
	global_load_lds_dwordx4 v247, s[8:9]
	s_add_u32 s8, s16, s46
	s_addc_u32 s9, s17, s47
	s_mov_b32 m0, s30
	s_nop 0
	global_load_lds_dwordx4 v248, s[8:9]
	s_mov_b32 m0, s31
	s_nop 0
	global_load_lds_dwordx4 v247, s[8:9]
	s_waitcnt vmcnt(6)
	s_waitcnt lgkmcnt(0)
	s_barrier
	s_setprio 1
	s_waitcnt lgkmcnt(0)
	v_mfma_f32_16x16x32_bf16 v[68:71], v[136:139], v[168:171], v[68:71]
	v_mfma_f32_16x16x32_bf16 v[68:71], v[140:143], v[172:175], v[68:71]
	v_mfma_f32_16x16x32_bf16 v[72:75], v[144:147], v[168:171], v[72:75]
	v_mfma_f32_16x16x32_bf16 v[72:75], v[148:151], v[172:175], v[72:75]
	v_mfma_f32_16x16x32_bf16 v[76:79], v[136:139], v[176:179], v[76:79]
	v_mfma_f32_16x16x32_bf16 v[76:79], v[140:143], v[180:183], v[76:79]
	v_mfma_f32_16x16x32_bf16 v[80:83], v[144:147], v[176:179], v[80:83]
	v_mfma_f32_16x16x32_bf16 v[80:83], v[148:151], v[180:183], v[80:83]
	v_mfma_f32_16x16x32_bf16 v[84:87], v[136:139], v[184:187], v[84:87]
	v_mfma_f32_16x16x32_bf16 v[84:87], v[140:143], v[188:191], v[84:87]
	v_mfma_f32_16x16x32_bf16 v[88:91], v[144:147], v[184:187], v[88:91]
	v_mfma_f32_16x16x32_bf16 v[88:91], v[148:151], v[188:191], v[88:91]
	v_mfma_f32_16x16x32_bf16 v[92:95], v[136:139], v[192:195], v[92:95]
	v_mfma_f32_16x16x32_bf16 v[92:95], v[140:143], v[196:199], v[92:95]
	v_mfma_f32_16x16x32_bf16 v[96:99], v[144:147], v[192:195], v[96:99]
	v_mfma_f32_16x16x32_bf16 v[96:99], v[148:151], v[196:199], v[96:99]
	s_setprio 0
	s_setprio 1
	v_mfma_f32_16x16x32_bf16 v[100:103], v[152:155], v[168:171], v[100:103]
	v_mfma_f32_16x16x32_bf16 v[100:103], v[156:159], v[172:175], v[100:103]
	v_mfma_f32_16x16x32_bf16 v[104:107], v[160:163], v[168:171], v[104:107]
	v_mfma_f32_16x16x32_bf16 v[104:107], v[164:167], v[172:175], v[104:107]
	v_mfma_f32_16x16x32_bf16 v[108:111], v[152:155], v[176:179], v[108:111]
	v_mfma_f32_16x16x32_bf16 v[108:111], v[156:159], v[180:183], v[108:111]
	v_mfma_f32_16x16x32_bf16 v[112:115], v[160:163], v[176:179], v[112:115]
	v_mfma_f32_16x16x32_bf16 v[112:115], v[164:167], v[180:183], v[112:115]
	v_mfma_f32_16x16x32_bf16 v[116:119], v[152:155], v[184:187], v[116:119]
	v_mfma_f32_16x16x32_bf16 v[116:119], v[156:159], v[188:191], v[116:119]
	v_mfma_f32_16x16x32_bf16 v[120:123], v[160:163], v[184:187], v[120:123]
	v_mfma_f32_16x16x32_bf16 v[120:123], v[164:167], v[188:191], v[120:123]
	v_mfma_f32_16x16x32_bf16 v[124:127], v[152:155], v[192:195], v[124:127]
	v_mfma_f32_16x16x32_bf16 v[124:127], v[156:159], v[196:199], v[124:127]
	v_mfma_f32_16x16x32_bf16 v[128:131], v[160:163], v[192:195], v[128:131]
	v_mfma_f32_16x16x32_bf16 v[128:131], v[164:167], v[196:199], v[128:131]
	s_setprio 0
	s_barrier
	ds_read_b128 v[136:139], v134
	ds_read_b128 v[140:143], v134 offset:1024
	ds_read_b128 v[144:147], v134 offset:2048
	ds_read_b128 v[148:151], v134 offset:3072
	ds_read_b128 v[152:155], v135
	ds_read_b128 v[156:159], v135 offset:1024
	ds_read_b128 v[160:163], v135 offset:2048
	ds_read_b128 v[164:167], v135 offset:3072
	s_mov_b32 m0, s7
	s_mov_b64 s[8:9], s[20:21]
	ds_read_b128 v[168:171], v246 offset:32768
	ds_read_b128 v[172:175], v246 offset:33792
	ds_read_b128 v[176:179], v246 offset:34816
	ds_read_b128 v[180:183], v246 offset:35840
	ds_read_b128 v[184:187], v246 offset:36864
	ds_read_b128 v[188:191], v246 offset:37888
	ds_read_b128 v[192:195], v246 offset:38912
	ds_read_b128 v[196:199], v246 offset:39936
	s_nop 0
	global_load_lds_dwordx4 v242, s[8:9]
	s_mov_b32 m0, s58
	s_nop 0
	global_load_lds_dwordx4 v2, s[8:9]
	s_add_u32 s8, s20, s46
	s_addc_u32 s9, s21, s47
	s_mov_b32 m0, s59
	s_nop 0
	global_load_lds_dwordx4 v242, s[8:9]
	s_mov_b64 s[100:101], s[8:9]
	s_waitcnt vmcnt(7)
	s_waitcnt lgkmcnt(0)
	s_barrier
	s_setprio 1
	s_waitcnt lgkmcnt(0)
	v_mfma_f32_16x16x32_bf16 v[4:7], v[136:139], v[168:171], v[4:7]
	v_mfma_f32_16x16x32_bf16 v[4:7], v[140:143], v[172:175], v[4:7]
	v_mfma_f32_16x16x32_bf16 v[8:11], v[144:147], v[168:171], v[8:11]
	v_mfma_f32_16x16x32_bf16 v[8:11], v[148:151], v[172:175], v[8:11]
	v_mfma_f32_16x16x32_bf16 v[12:15], v[136:139], v[176:179], v[12:15]
	v_mfma_f32_16x16x32_bf16 v[12:15], v[140:143], v[180:183], v[12:15]
	v_mfma_f32_16x16x32_bf16 v[16:19], v[144:147], v[176:179], v[16:19]
	v_mfma_f32_16x16x32_bf16 v[16:19], v[148:151], v[180:183], v[16:19]
	v_mfma_f32_16x16x32_bf16 v[20:23], v[136:139], v[184:187], v[20:23]
	v_mfma_f32_16x16x32_bf16 v[20:23], v[140:143], v[188:191], v[20:23]
	v_mfma_f32_16x16x32_bf16 v[24:27], v[144:147], v[184:187], v[24:27]
	v_mfma_f32_16x16x32_bf16 v[24:27], v[148:151], v[188:191], v[24:27]
	v_mfma_f32_16x16x32_bf16 v[28:31], v[136:139], v[192:195], v[28:31]
	v_mfma_f32_16x16x32_bf16 v[28:31], v[140:143], v[196:199], v[28:31]
	v_mfma_f32_16x16x32_bf16 v[32:35], v[144:147], v[192:195], v[32:35]
	v_mfma_f32_16x16x32_bf16 v[32:35], v[148:151], v[196:199], v[32:35]
	s_setprio 0
	s_setprio 1
	v_mfma_f32_16x16x32_bf16 v[36:39], v[152:155], v[168:171], v[36:39]
	v_mfma_f32_16x16x32_bf16 v[36:39], v[156:159], v[172:175], v[36:39]
	v_mfma_f32_16x16x32_bf16 v[40:43], v[160:163], v[168:171], v[40:43]
	v_mfma_f32_16x16x32_bf16 v[40:43], v[164:167], v[172:175], v[40:43]
	v_mfma_f32_16x16x32_bf16 v[44:47], v[152:155], v[176:179], v[44:47]
	v_mfma_f32_16x16x32_bf16 v[44:47], v[156:159], v[180:183], v[44:47]
	v_mfma_f32_16x16x32_bf16 v[48:51], v[160:163], v[176:179], v[48:51]
	v_mfma_f32_16x16x32_bf16 v[48:51], v[164:167], v[180:183], v[48:51]
	v_mfma_f32_16x16x32_bf16 v[52:55], v[152:155], v[184:187], v[52:55]
	v_mfma_f32_16x16x32_bf16 v[52:55], v[156:159], v[188:191], v[52:55]
	v_mfma_f32_16x16x32_bf16 v[56:59], v[160:163], v[184:187], v[56:59]
	v_mfma_f32_16x16x32_bf16 v[56:59], v[164:167], v[188:191], v[56:59]
	v_mfma_f32_16x16x32_bf16 v[60:63], v[152:155], v[192:195], v[60:63]
	v_mfma_f32_16x16x32_bf16 v[60:63], v[156:159], v[196:199], v[60:63]
	v_mfma_f32_16x16x32_bf16 v[64:67], v[160:163], v[192:195], v[64:67]
	v_mfma_f32_16x16x32_bf16 v[64:67], v[164:167], v[196:199], v[64:67]
	s_setprio 0
	s_barrier
	s_mov_b32 m0, s69
	s_nop 0
	global_load_lds_dwordx4 v2, s[100:101]
	s_mov_b32 m0, s84
	s_mov_b64 s[8:9], s[18:19]
	ds_read_b128 v[168:171], v246 offset:49152
	ds_read_b128 v[172:175], v246 offset:50176
	ds_read_b128 v[176:179], v246 offset:51200
	ds_read_b128 v[180:183], v246 offset:52224
	ds_read_b128 v[184:187], v246 offset:53248
	ds_read_b128 v[188:191], v246 offset:54272
	ds_read_b128 v[192:195], v246 offset:55296
	ds_read_b128 v[196:199], v246 offset:56320
	s_nop 0
	global_load_lds_dwordx4 v248, s[8:9]
	s_mov_b32 m0, s85
	s_nop 0
	global_load_lds_dwordx4 v247, s[8:9]
	s_add_u32 s8, s18, s46
	s_addc_u32 s9, s19, s47
	s_mov_b32 m0, s28
	s_nop 0
	global_load_lds_dwordx4 v248, s[8:9]
	s_mov_b32 m0, s29
	s_nop 0
	global_load_lds_dwordx4 v247, s[8:9]
	s_waitcnt vmcnt(6)
	s_waitcnt lgkmcnt(0)
	s_barrier
	s_setprio 1
	s_waitcnt lgkmcnt(0)
	v_mfma_f32_16x16x32_bf16 v[68:71], v[136:139], v[168:171], v[68:71]
	v_mfma_f32_16x16x32_bf16 v[68:71], v[140:143], v[172:175], v[68:71]
	v_mfma_f32_16x16x32_bf16 v[72:75], v[144:147], v[168:171], v[72:75]
	v_mfma_f32_16x16x32_bf16 v[72:75], v[148:151], v[172:175], v[72:75]
	v_mfma_f32_16x16x32_bf16 v[76:79], v[136:139], v[176:179], v[76:79]
	v_mfma_f32_16x16x32_bf16 v[76:79], v[140:143], v[180:183], v[76:79]
	v_mfma_f32_16x16x32_bf16 v[80:83], v[144:147], v[176:179], v[80:83]
	v_mfma_f32_16x16x32_bf16 v[80:83], v[148:151], v[180:183], v[80:83]
	v_mfma_f32_16x16x32_bf16 v[84:87], v[136:139], v[184:187], v[84:87]
	v_mfma_f32_16x16x32_bf16 v[84:87], v[140:143], v[188:191], v[84:87]
	v_mfma_f32_16x16x32_bf16 v[88:91], v[144:147], v[184:187], v[88:91]
	v_mfma_f32_16x16x32_bf16 v[88:91], v[148:151], v[188:191], v[88:91]
	v_mfma_f32_16x16x32_bf16 v[92:95], v[136:139], v[192:195], v[92:95]
	v_mfma_f32_16x16x32_bf16 v[92:95], v[140:143], v[196:199], v[92:95]
	v_mfma_f32_16x16x32_bf16 v[96:99], v[144:147], v[192:195], v[96:99]
	v_mfma_f32_16x16x32_bf16 v[96:99], v[148:151], v[196:199], v[96:99]
	s_setprio 0
	s_setprio 1
	v_mfma_f32_16x16x32_bf16 v[100:103], v[152:155], v[168:171], v[100:103]
	v_mfma_f32_16x16x32_bf16 v[100:103], v[156:159], v[172:175], v[100:103]
	v_mfma_f32_16x16x32_bf16 v[104:107], v[160:163], v[168:171], v[104:107]
	v_mfma_f32_16x16x32_bf16 v[104:107], v[164:167], v[172:175], v[104:107]
	v_mfma_f32_16x16x32_bf16 v[108:111], v[152:155], v[176:179], v[108:111]
	v_mfma_f32_16x16x32_bf16 v[108:111], v[156:159], v[180:183], v[108:111]
	v_mfma_f32_16x16x32_bf16 v[112:115], v[160:163], v[176:179], v[112:115]
	v_mfma_f32_16x16x32_bf16 v[112:115], v[164:167], v[180:183], v[112:115]
	v_mfma_f32_16x16x32_bf16 v[116:119], v[152:155], v[184:187], v[116:119]
	v_mfma_f32_16x16x32_bf16 v[116:119], v[156:159], v[188:191], v[116:119]
	v_mfma_f32_16x16x32_bf16 v[120:123], v[160:163], v[184:187], v[120:123]
	v_mfma_f32_16x16x32_bf16 v[120:123], v[164:167], v[188:191], v[120:123]
	v_mfma_f32_16x16x32_bf16 v[124:127], v[152:155], v[192:195], v[124:127]
	v_mfma_f32_16x16x32_bf16 v[124:127], v[156:159], v[196:199], v[124:127]
	v_mfma_f32_16x16x32_bf16 v[128:131], v[160:163], v[192:195], v[128:131]
	v_mfma_f32_16x16x32_bf16 v[128:131], v[164:167], v[196:199], v[128:131]
	s_setprio 0
	s_barrier
	s_add_i32 s8, s88, 2
	s_add_u32 s86, s86, 0x100
	s_addc_u32 s87, s87, 0
	s_add_u32 s26, s26, 0x100
	s_addc_u32 s27, s27, 0
	s_cmp_ge_i32 s88, s4
	s_mov_b32 s88, s8
	s_cbranch_scc0 .LBB0_880

.LBB0_1021:
	ds_read_b128 v[144:147], v132
	ds_read_b128 v[148:151], v132 offset:1024
	ds_read_b128 v[152:155], v132 offset:2048
	ds_read_b128 v[156:159], v132 offset:3072
	ds_read_b128 v[160:163], v133
	ds_read_b128 v[164:167], v133 offset:1024
	ds_read_b128 v[168:171], v133 offset:2048
	ds_read_b128 v[172:175], v133 offset:3072
	s_cmp_eq_u32 s76, s97
	s_cselect_b32 s17, s43, s96
	s_cselect_b32 s16, s42, s95
	s_cselect_b32 s67, s65, s73
	s_cselect_b32 s66, s64, s72
	s_add_u32 s8, s72, 0xffffff80
	s_addc_u32 s9, s73, -1
	s_mov_b32 m0, s85
	s_mov_b64 s[18:19], s[8:9]
	ds_read_b128 v[176:179], v141 offset:8192
	ds_read_b128 v[180:183], v141 offset:9216
	ds_read_b128 v[184:187], v141 offset:10240
	ds_read_b128 v[188:191], v141 offset:11264
	ds_read_b128 v[192:195], v141 offset:12288
	ds_read_b128 v[196:199], v141 offset:13312
	ds_read_b128 v[200:203], v141 offset:14336
	ds_read_b128 v[204:207], v141 offset:15360
	s_add_u32 s8, s8, s20
	global_load_lds_dwordx4 v137, s[18:19]
	s_mov_b32 m0, s86
	s_addc_u32 s9, s9, s21
	global_load_lds_dwordx4 v136, s[18:19]
	s_mov_b32 m0, s87
	s_add_u32 s18, s16, 0x80
	global_load_lds_dwordx4 v137, s[8:9]
	s_addc_u32 s19, s17, 0
	s_mov_b64 s[100:101], s[8:9]
	s_waitcnt vmcnt(7)
	s_waitcnt lgkmcnt(0)
	s_barrier
	s_setprio 1
	s_waitcnt lgkmcnt(0)
	v_mfma_f32_16x16x32_bf16 v[4:7], v[144:147], v[176:179], v[4:7]
	v_mfma_f32_16x16x32_bf16 v[4:7], v[148:151], v[180:183], v[4:7]
	v_mfma_f32_16x16x32_bf16 v[8:11], v[152:155], v[176:179], v[8:11]
	v_mfma_f32_16x16x32_bf16 v[8:11], v[156:159], v[180:183], v[8:11]
	v_mfma_f32_16x16x32_bf16 v[12:15], v[144:147], v[184:187], v[12:15]
	v_mfma_f32_16x16x32_bf16 v[12:15], v[148:151], v[188:191], v[12:15]
	v_mfma_f32_16x16x32_bf16 v[16:19], v[152:155], v[184:187], v[16:19]
	v_mfma_f32_16x16x32_bf16 v[16:19], v[156:159], v[188:191], v[16:19]
	v_mfma_f32_16x16x32_bf16 v[20:23], v[144:147], v[192:195], v[20:23]
	v_mfma_f32_16x16x32_bf16 v[20:23], v[148:151], v[196:199], v[20:23]
	v_mfma_f32_16x16x32_bf16 v[24:27], v[152:155], v[192:195], v[24:27]
	v_mfma_f32_16x16x32_bf16 v[24:27], v[156:159], v[196:199], v[24:27]
	v_mfma_f32_16x16x32_bf16 v[28:31], v[144:147], v[200:203], v[28:31]
	v_mfma_f32_16x16x32_bf16 v[28:31], v[148:151], v[204:207], v[28:31]
	v_mfma_f32_16x16x32_bf16 v[32:35], v[152:155], v[200:203], v[32:35]
	v_mfma_f32_16x16x32_bf16 v[32:35], v[156:159], v[204:207], v[32:35]
	s_setprio 0
	s_setprio 1
	v_mfma_f32_16x16x32_bf16 v[36:39], v[160:163], v[176:179], v[36:39]
	v_mfma_f32_16x16x32_bf16 v[36:39], v[164:167], v[180:183], v[36:39]
	v_mfma_f32_16x16x32_bf16 v[40:43], v[168:171], v[176:179], v[40:43]
	v_mfma_f32_16x16x32_bf16 v[40:43], v[172:175], v[180:183], v[40:43]
	v_mfma_f32_16x16x32_bf16 v[44:47], v[160:163], v[184:187], v[44:47]
	v_mfma_f32_16x16x32_bf16 v[44:47], v[164:167], v[188:191], v[44:47]
	v_mfma_f32_16x16x32_bf16 v[48:51], v[168:171], v[184:187], v[48:51]
	v_mfma_f32_16x16x32_bf16 v[48:51], v[172:175], v[188:191], v[48:51]
	v_mfma_f32_16x16x32_bf16 v[52:55], v[160:163], v[192:195], v[52:55]
	v_mfma_f32_16x16x32_bf16 v[52:55], v[164:167], v[196:199], v[52:55]
	v_mfma_f32_16x16x32_bf16 v[56:59], v[168:171], v[192:195], v[56:59]
	v_mfma_f32_16x16x32_bf16 v[56:59], v[172:175], v[196:199], v[56:59]
	v_mfma_f32_16x16x32_bf16 v[60:63], v[160:163], v[200:203], v[60:63]
	v_mfma_f32_16x16x32_bf16 v[60:63], v[164:167], v[204:207], v[60:63]
	v_mfma_f32_16x16x32_bf16 v[64:67], v[168:171], v[200:203], v[64:67]
	v_mfma_f32_16x16x32_bf16 v[64:67], v[172:175], v[204:207], v[64:67]
	s_setprio 0
	s_barrier
	s_mov_b32 m0, s88
	s_nop 0
	global_load_lds_dwordx4 v136, s[100:101]
	s_mov_b32 m0, s89
	s_mov_b64 s[8:9], s[16:17]
	ds_read_b128 v[176:179], v141 offset:24576
	ds_read_b128 v[180:183], v141 offset:25600
	ds_read_b128 v[184:187], v141 offset:26624
	ds_read_b128 v[188:191], v141 offset:27648
	ds_read_b128 v[192:195], v141 offset:28672
	ds_read_b128 v[196:199], v141 offset:29696
	ds_read_b128 v[200:203], v141 offset:30720
	ds_read_b128 v[204:207], v141 offset:31744
	s_nop 0
	global_load_lds_dwordx4 v143, s[8:9]
	s_mov_b32 m0, s90
	s_nop 0
	global_load_lds_dwordx4 v142, s[8:9]
	s_add_u32 s8, s16, s20
	s_addc_u32 s9, s17, s21
	s_mov_b32 m0, s91
	s_nop 0
	global_load_lds_dwordx4 v143, s[8:9]
	s_mov_b32 m0, s92
	s_nop 0
	global_load_lds_dwordx4 v142, s[8:9]
	s_waitcnt vmcnt(6)
	s_waitcnt lgkmcnt(0)
	s_barrier
	s_setprio 1
	s_waitcnt lgkmcnt(0)
	v_mfma_f32_16x16x32_bf16 v[68:71], v[144:147], v[176:179], v[68:71]
	v_mfma_f32_16x16x32_bf16 v[68:71], v[148:151], v[180:183], v[68:71]
	v_mfma_f32_16x16x32_bf16 v[72:75], v[152:155], v[176:179], v[72:75]
	v_mfma_f32_16x16x32_bf16 v[72:75], v[156:159], v[180:183], v[72:75]
	v_mfma_f32_16x16x32_bf16 v[76:79], v[144:147], v[184:187], v[76:79]
	v_mfma_f32_16x16x32_bf16 v[76:79], v[148:151], v[188:191], v[76:79]
	v_mfma_f32_16x16x32_bf16 v[80:83], v[152:155], v[184:187], v[80:83]
	v_mfma_f32_16x16x32_bf16 v[80:83], v[156:159], v[188:191], v[80:83]
	v_mfma_f32_16x16x32_bf16 v[84:87], v[144:147], v[192:195], v[84:87]
	v_mfma_f32_16x16x32_bf16 v[84:87], v[148:151], v[196:199], v[84:87]
	v_mfma_f32_16x16x32_bf16 v[88:91], v[152:155], v[192:195], v[88:91]
	v_mfma_f32_16x16x32_bf16 v[88:91], v[156:159], v[196:199], v[88:91]
	v_mfma_f32_16x16x32_bf16 v[92:95], v[144:147], v[200:203], v[92:95]
	v_mfma_f32_16x16x32_bf16 v[92:95], v[148:151], v[204:207], v[92:95]
	v_mfma_f32_16x16x32_bf16 v[96:99], v[152:155], v[200:203], v[96:99]
	v_mfma_f32_16x16x32_bf16 v[96:99], v[156:159], v[204:207], v[96:99]
	s_setprio 0
	s_setprio 1
	v_mfma_f32_16x16x32_bf16 v[100:103], v[160:163], v[176:179], v[100:103]
	v_mfma_f32_16x16x32_bf16 v[100:103], v[164:167], v[180:183], v[100:103]
	v_mfma_f32_16x16x32_bf16 v[104:107], v[168:171], v[176:179], v[104:107]
	v_mfma_f32_16x16x32_bf16 v[104:107], v[172:175], v[180:183], v[104:107]
	v_mfma_f32_16x16x32_bf16 v[108:111], v[160:163], v[184:187], v[108:111]
	v_mfma_f32_16x16x32_bf16 v[108:111], v[164:167], v[188:191], v[108:111]
	v_mfma_f32_16x16x32_bf16 v[112:115], v[168:171], v[184:187], v[112:115]
	v_mfma_f32_16x16x32_bf16 v[112:115], v[172:175], v[188:191], v[112:115]
	v_mfma_f32_16x16x32_bf16 v[116:119], v[160:163], v[192:195], v[116:119]
	v_mfma_f32_16x16x32_bf16 v[116:119], v[164:167], v[196:199], v[116:119]
	v_mfma_f32_16x16x32_bf16 v[120:123], v[168:171], v[192:195], v[120:123]
	v_mfma_f32_16x16x32_bf16 v[120:123], v[172:175], v[196:199], v[120:123]
	v_mfma_f32_16x16x32_bf16 v[124:127], v[160:163], v[200:203], v[124:127]
	v_mfma_f32_16x16x32_bf16 v[124:127], v[164:167], v[204:207], v[124:127]
	v_mfma_f32_16x16x32_bf16 v[128:131], v[168:171], v[200:203], v[128:131]
	v_mfma_f32_16x16x32_bf16 v[128:131], v[172:175], v[204:207], v[128:131]
	s_setprio 0
	s_barrier
	ds_read_b128 v[144:147], v134
	ds_read_b128 v[148:151], v134 offset:1024
	ds_read_b128 v[152:155], v134 offset:2048
	ds_read_b128 v[156:159], v134 offset:3072
	ds_read_b128 v[160:163], v135
	ds_read_b128 v[164:167], v135 offset:1024
	ds_read_b128 v[168:171], v135 offset:2048
	ds_read_b128 v[172:175], v135 offset:3072
	s_mov_b32 m0, s78
	s_mov_b64 s[8:9], s[66:67]
	ds_read_b128 v[176:179], v141 offset:40960
	ds_read_b128 v[180:183], v141 offset:41984
	ds_read_b128 v[184:187], v141 offset:43008
	ds_read_b128 v[188:191], v141 offset:44032
	ds_read_b128 v[192:195], v141 offset:45056
	ds_read_b128 v[196:199], v141 offset:46080
	ds_read_b128 v[200:203], v141 offset:47104
	ds_read_b128 v[204:207], v141 offset:48128
	s_nop 0
	global_load_lds_dwordx4 v137, s[8:9]
	s_mov_b32 m0, s79
	s_nop 0
	global_load_lds_dwordx4 v136, s[8:9]
	s_add_u32 s8, s66, s20
	s_addc_u32 s9, s67, s21
	s_mov_b32 m0, s80
	s_nop 0
	global_load_lds_dwordx4 v137, s[8:9]
	s_mov_b64 s[100:101], s[8:9]
	s_waitcnt vmcnt(7)
	s_waitcnt lgkmcnt(0)
	s_barrier
	s_setprio 1
	s_waitcnt lgkmcnt(0)
	v_mfma_f32_16x16x32_bf16 v[4:7], v[144:147], v[176:179], v[4:7]
	v_mfma_f32_16x16x32_bf16 v[4:7], v[148:151], v[180:183], v[4:7]
	v_mfma_f32_16x16x32_bf16 v[8:11], v[152:155], v[176:179], v[8:11]
	v_mfma_f32_16x16x32_bf16 v[8:11], v[156:159], v[180:183], v[8:11]
	v_mfma_f32_16x16x32_bf16 v[12:15], v[144:147], v[184:187], v[12:15]
	v_mfma_f32_16x16x32_bf16 v[12:15], v[148:151], v[188:191], v[12:15]
	v_mfma_f32_16x16x32_bf16 v[16:19], v[152:155], v[184:187], v[16:19]
	v_mfma_f32_16x16x32_bf16 v[16:19], v[156:159], v[188:191], v[16:19]
	v_mfma_f32_16x16x32_bf16 v[20:23], v[144:147], v[192:195], v[20:23]
	v_mfma_f32_16x16x32_bf16 v[20:23], v[148:151], v[196:199], v[20:23]
	v_mfma_f32_16x16x32_bf16 v[24:27], v[152:155], v[192:195], v[24:27]
	v_mfma_f32_16x16x32_bf16 v[24:27], v[156:159], v[196:199], v[24:27]
	v_mfma_f32_16x16x32_bf16 v[28:31], v[144:147], v[200:203], v[28:31]
	v_mfma_f32_16x16x32_bf16 v[28:31], v[148:151], v[204:207], v[28:31]
	v_mfma_f32_16x16x32_bf16 v[32:35], v[152:155], v[200:203], v[32:35]
	v_mfma_f32_16x16x32_bf16 v[32:35], v[156:159], v[204:207], v[32:35]
	s_setprio 0
	s_setprio 1
	v_mfma_f32_16x16x32_bf16 v[36:39], v[160:163], v[176:179], v[36:39]
	v_mfma_f32_16x16x32_bf16 v[36:39], v[164:167], v[180:183], v[36:39]
	v_mfma_f32_16x16x32_bf16 v[40:43], v[168:171], v[176:179], v[40:43]
	v_mfma_f32_16x16x32_bf16 v[40:43], v[172:175], v[180:183], v[40:43]
	v_mfma_f32_16x16x32_bf16 v[44:47], v[160:163], v[184:187], v[44:47]
	v_mfma_f32_16x16x32_bf16 v[44:47], v[164:167], v[188:191], v[44:47]
	v_mfma_f32_16x16x32_bf16 v[48:51], v[168:171], v[184:187], v[48:51]
	v_mfma_f32_16x16x32_bf16 v[48:51], v[172:175], v[188:191], v[48:51]
	v_mfma_f32_16x16x32_bf16 v[52:55], v[160:163], v[192:195], v[52:55]
	v_mfma_f32_16x16x32_bf16 v[52:55], v[164:167], v[196:199], v[52:55]
	v_mfma_f32_16x16x32_bf16 v[56:59], v[168:171], v[192:195], v[56:59]
	v_mfma_f32_16x16x32_bf16 v[56:59], v[172:175], v[196:199], v[56:59]
	v_mfma_f32_16x16x32_bf16 v[60:63], v[160:163], v[200:203], v[60:63]
	v_mfma_f32_16x16x32_bf16 v[60:63], v[164:167], v[204:207], v[60:63]
	v_mfma_f32_16x16x32_bf16 v[64:67], v[168:171], v[200:203], v[64:67]
	v_mfma_f32_16x16x32_bf16 v[64:67], v[172:175], v[204:207], v[64:67]
	s_setprio 0
	s_barrier
	s_mov_b32 m0, s81
	s_nop 0
	global_load_lds_dwordx4 v136, s[100:101]
	s_mov_b32 m0, s68
	s_mov_b64 s[8:9], s[18:19]
	ds_read_b128 v[176:179], v141 offset:57344
	ds_read_b128 v[180:183], v141 offset:58368
	ds_read_b128 v[184:187], v141 offset:59392
	ds_read_b128 v[188:191], v141 offset:60416
	ds_read_b128 v[192:195], v141 offset:61440
	ds_read_b128 v[196:199], v141 offset:62464
	ds_read_b128 v[200:203], v141 offset:63488
	ds_read_b128 v[204:207], v141 offset:64512
	s_nop 0
	global_load_lds_dwordx4 v143, s[8:9]
	s_mov_b32 m0, s69
	s_nop 0
	global_load_lds_dwordx4 v142, s[8:9]
	s_add_u32 s8, s18, s20
	s_addc_u32 s9, s19, s21
	s_mov_b32 m0, s93
	s_nop 0
	global_load_lds_dwordx4 v143, s[8:9]
	s_mov_b32 m0, s94
	s_nop 0
	global_load_lds_dwordx4 v142, s[8:9]
	s_waitcnt vmcnt(6)
	s_waitcnt lgkmcnt(0)
	s_barrier
	s_setprio 1
	s_waitcnt lgkmcnt(0)
	v_mfma_f32_16x16x32_bf16 v[68:71], v[144:147], v[176:179], v[68:71]
	v_mfma_f32_16x16x32_bf16 v[68:71], v[148:151], v[180:183], v[68:71]
	v_mfma_f32_16x16x32_bf16 v[72:75], v[152:155], v[176:179], v[72:75]
	v_mfma_f32_16x16x32_bf16 v[72:75], v[156:159], v[180:183], v[72:75]
	v_mfma_f32_16x16x32_bf16 v[76:79], v[144:147], v[184:187], v[76:79]
	v_mfma_f32_16x16x32_bf16 v[76:79], v[148:151], v[188:191], v[76:79]
	v_mfma_f32_16x16x32_bf16 v[80:83], v[152:155], v[184:187], v[80:83]
	v_mfma_f32_16x16x32_bf16 v[80:83], v[156:159], v[188:191], v[80:83]
	v_mfma_f32_16x16x32_bf16 v[84:87], v[144:147], v[192:195], v[84:87]
	v_mfma_f32_16x16x32_bf16 v[84:87], v[148:151], v[196:199], v[84:87]
	v_mfma_f32_16x16x32_bf16 v[88:91], v[152:155], v[192:195], v[88:91]
	v_mfma_f32_16x16x32_bf16 v[88:91], v[156:159], v[196:199], v[88:91]
	v_mfma_f32_16x16x32_bf16 v[92:95], v[144:147], v[200:203], v[92:95]
	v_mfma_f32_16x16x32_bf16 v[92:95], v[148:151], v[204:207], v[92:95]
	v_mfma_f32_16x16x32_bf16 v[96:99], v[152:155], v[200:203], v[96:99]
	v_mfma_f32_16x16x32_bf16 v[96:99], v[156:159], v[204:207], v[96:99]
	s_setprio 0
	s_setprio 1
	v_mfma_f32_16x16x32_bf16 v[100:103], v[160:163], v[176:179], v[100:103]
	v_mfma_f32_16x16x32_bf16 v[100:103], v[164:167], v[180:183], v[100:103]
	v_mfma_f32_16x16x32_bf16 v[104:107], v[168:171], v[176:179], v[104:107]
	v_mfma_f32_16x16x32_bf16 v[104:107], v[172:175], v[180:183], v[104:107]
	v_mfma_f32_16x16x32_bf16 v[108:111], v[160:163], v[184:187], v[108:111]
	v_mfma_f32_16x16x32_bf16 v[108:111], v[164:167], v[188:191], v[108:111]
	v_mfma_f32_16x16x32_bf16 v[112:115], v[168:171], v[184:187], v[112:115]
	v_mfma_f32_16x16x32_bf16 v[112:115], v[172:175], v[188:191], v[112:115]
	v_mfma_f32_16x16x32_bf16 v[116:119], v[160:163], v[192:195], v[116:119]
	v_mfma_f32_16x16x32_bf16 v[116:119], v[164:167], v[196:199], v[116:119]
	v_mfma_f32_16x16x32_bf16 v[120:123], v[168:171], v[192:195], v[120:123]
	v_mfma_f32_16x16x32_bf16 v[120:123], v[172:175], v[196:199], v[120:123]
	v_mfma_f32_16x16x32_bf16 v[124:127], v[160:163], v[200:203], v[124:127]
	v_mfma_f32_16x16x32_bf16 v[124:127], v[164:167], v[204:207], v[124:127]
	v_mfma_f32_16x16x32_bf16 v[128:131], v[168:171], v[200:203], v[128:131]
	v_mfma_f32_16x16x32_bf16 v[128:131], v[172:175], v[204:207], v[128:131]
	s_setprio 0
	s_barrier
	s_add_i32 s8, s97, 2
	s_add_u32 s95, s95, 0x100
	s_addc_u32 s96, s96, 0
	s_add_u32 s72, s72, 0x100
	s_addc_u32 s73, s73, 0
	s_cmp_ge_i32 s97, s76
	s_mov_b32 s97, s8
	s_cbranch_scc0 .LBB0_1021
	v_readlane_b32 s96, v255, 41
	v_readlane_b32 s97, v255, 42

.LBB0_1042:
	ds_read_b128 v[144:147], v132
	ds_read_b128 v[148:151], v132 offset:1024
	ds_read_b128 v[152:155], v132 offset:2048
	ds_read_b128 v[156:159], v132 offset:3072
	ds_read_b128 v[160:163], v133
	ds_read_b128 v[164:167], v133 offset:1024
	ds_read_b128 v[168:171], v133 offset:2048
	ds_read_b128 v[172:175], v133 offset:3072
	s_cmp_eq_u32 s72, s95
	s_cselect_b32 s17, s43, s94
	s_cselect_b32 s16, s42, s93
	s_cselect_b32 s65, s41, s67
	s_cselect_b32 s64, s40, s66
	s_add_u32 s8, s66, 0xffffff80
	s_addc_u32 s9, s67, -1
	s_mov_b32 m0, s83
	s_mov_b64 s[18:19], s[8:9]
	ds_read_b128 v[176:179], v141
	ds_read_b128 v[180:183], v141 offset:1024
	ds_read_b128 v[184:187], v141 offset:2048
	ds_read_b128 v[188:191], v141 offset:3072
	ds_read_b128 v[192:195], v141 offset:4096
	ds_read_b128 v[196:199], v141 offset:5120
	ds_read_b128 v[200:203], v141 offset:6144
	ds_read_b128 v[204:207], v141 offset:7168
	s_add_u32 s8, s8, s20
	global_load_lds_dwordx4 v137, s[18:19]
	s_mov_b32 m0, s84
	s_addc_u32 s9, s9, s21
	global_load_lds_dwordx4 v136, s[18:19]
	s_mov_b32 m0, s85
	s_add_u32 s18, s16, 0x80
	global_load_lds_dwordx4 v137, s[8:9]
	s_addc_u32 s19, s17, 0
	s_mov_b64 s[100:101], s[8:9]
	s_waitcnt vmcnt(7)
	s_waitcnt lgkmcnt(0)
	s_barrier
	s_setprio 1
	s_waitcnt lgkmcnt(0)
	v_mfma_f32_16x16x32_bf16 v[4:7], v[144:147], v[176:179], v[4:7]
	v_mfma_f32_16x16x32_bf16 v[4:7], v[148:151], v[180:183], v[4:7]
	v_mfma_f32_16x16x32_bf16 v[8:11], v[152:155], v[176:179], v[8:11]
	v_mfma_f32_16x16x32_bf16 v[8:11], v[156:159], v[180:183], v[8:11]
	v_mfma_f32_16x16x32_bf16 v[12:15], v[144:147], v[184:187], v[12:15]
	v_mfma_f32_16x16x32_bf16 v[12:15], v[148:151], v[188:191], v[12:15]
	v_mfma_f32_16x16x32_bf16 v[16:19], v[152:155], v[184:187], v[16:19]
	v_mfma_f32_16x16x32_bf16 v[16:19], v[156:159], v[188:191], v[16:19]
	v_mfma_f32_16x16x32_bf16 v[20:23], v[144:147], v[192:195], v[20:23]
	v_mfma_f32_16x16x32_bf16 v[20:23], v[148:151], v[196:199], v[20:23]
	v_mfma_f32_16x16x32_bf16 v[24:27], v[152:155], v[192:195], v[24:27]
	v_mfma_f32_16x16x32_bf16 v[24:27], v[156:159], v[196:199], v[24:27]
	v_mfma_f32_16x16x32_bf16 v[28:31], v[144:147], v[200:203], v[28:31]
	v_mfma_f32_16x16x32_bf16 v[28:31], v[148:151], v[204:207], v[28:31]
	v_mfma_f32_16x16x32_bf16 v[32:35], v[152:155], v[200:203], v[32:35]
	v_mfma_f32_16x16x32_bf16 v[32:35], v[156:159], v[204:207], v[32:35]
	s_setprio 0
	s_setprio 1
	v_mfma_f32_16x16x32_bf16 v[36:39], v[160:163], v[176:179], v[36:39]
	v_mfma_f32_16x16x32_bf16 v[36:39], v[164:167], v[180:183], v[36:39]
	v_mfma_f32_16x16x32_bf16 v[40:43], v[168:171], v[176:179], v[40:43]
	v_mfma_f32_16x16x32_bf16 v[40:43], v[172:175], v[180:183], v[40:43]
	v_mfma_f32_16x16x32_bf16 v[44:47], v[160:163], v[184:187], v[44:47]
	v_mfma_f32_16x16x32_bf16 v[44:47], v[164:167], v[188:191], v[44:47]
	v_mfma_f32_16x16x32_bf16 v[48:51], v[168:171], v[184:187], v[48:51]
	v_mfma_f32_16x16x32_bf16 v[48:51], v[172:175], v[188:191], v[48:51]
	v_mfma_f32_16x16x32_bf16 v[52:55], v[160:163], v[192:195], v[52:55]
	v_mfma_f32_16x16x32_bf16 v[52:55], v[164:167], v[196:199], v[52:55]
	v_mfma_f32_16x16x32_bf16 v[56:59], v[168:171], v[192:195], v[56:59]
	v_mfma_f32_16x16x32_bf16 v[56:59], v[172:175], v[196:199], v[56:59]
	v_mfma_f32_16x16x32_bf16 v[60:63], v[160:163], v[200:203], v[60:63]
	v_mfma_f32_16x16x32_bf16 v[60:63], v[164:167], v[204:207], v[60:63]
	v_mfma_f32_16x16x32_bf16 v[64:67], v[168:171], v[200:203], v[64:67]
	v_mfma_f32_16x16x32_bf16 v[64:67], v[172:175], v[204:207], v[64:67]
	s_setprio 0
	s_barrier
	s_mov_b32 m0, s86
	s_nop 0
	global_load_lds_dwordx4 v136, s[100:101]
	s_mov_b32 m0, s87
	s_mov_b64 s[8:9], s[16:17]
	ds_read_b128 v[176:179], v141 offset:16384
	ds_read_b128 v[180:183], v141 offset:17408
	ds_read_b128 v[184:187], v141 offset:18432
	ds_read_b128 v[188:191], v141 offset:19456
	ds_read_b128 v[192:195], v141 offset:20480
	ds_read_b128 v[196:199], v141 offset:21504
	ds_read_b128 v[200:203], v141 offset:22528
	ds_read_b128 v[204:207], v141 offset:23552
	s_nop 0
	global_load_lds_dwordx4 v143, s[8:9]
	s_mov_b32 m0, s88
	s_nop 0
	global_load_lds_dwordx4 v142, s[8:9]
	s_add_u32 s8, s16, s20
	s_addc_u32 s9, s17, s21
	s_mov_b32 m0, s89
	s_nop 0
	global_load_lds_dwordx4 v143, s[8:9]
	s_mov_b32 m0, s90
	s_nop 0
	global_load_lds_dwordx4 v142, s[8:9]
	s_waitcnt vmcnt(6)
	s_waitcnt lgkmcnt(0)
	s_barrier
	s_setprio 1
	s_waitcnt lgkmcnt(0)
	v_mfma_f32_16x16x32_bf16 v[68:71], v[144:147], v[176:179], v[68:71]
	v_mfma_f32_16x16x32_bf16 v[68:71], v[148:151], v[180:183], v[68:71]
	v_mfma_f32_16x16x32_bf16 v[72:75], v[152:155], v[176:179], v[72:75]
	v_mfma_f32_16x16x32_bf16 v[72:75], v[156:159], v[180:183], v[72:75]
	v_mfma_f32_16x16x32_bf16 v[76:79], v[144:147], v[184:187], v[76:79]
	v_mfma_f32_16x16x32_bf16 v[76:79], v[148:151], v[188:191], v[76:79]
	v_mfma_f32_16x16x32_bf16 v[80:83], v[152:155], v[184:187], v[80:83]
	v_mfma_f32_16x16x32_bf16 v[80:83], v[156:159], v[188:191], v[80:83]
	v_mfma_f32_16x16x32_bf16 v[84:87], v[144:147], v[192:195], v[84:87]
	v_mfma_f32_16x16x32_bf16 v[84:87], v[148:151], v[196:199], v[84:87]
	v_mfma_f32_16x16x32_bf16 v[88:91], v[152:155], v[192:195], v[88:91]
	v_mfma_f32_16x16x32_bf16 v[88:91], v[156:159], v[196:199], v[88:91]
	v_mfma_f32_16x16x32_bf16 v[92:95], v[144:147], v[200:203], v[92:95]
	v_mfma_f32_16x16x32_bf16 v[92:95], v[148:151], v[204:207], v[92:95]
	v_mfma_f32_16x16x32_bf16 v[96:99], v[152:155], v[200:203], v[96:99]
	v_mfma_f32_16x16x32_bf16 v[96:99], v[156:159], v[204:207], v[96:99]
	s_setprio 0
	s_setprio 1
	v_mfma_f32_16x16x32_bf16 v[100:103], v[160:163], v[176:179], v[100:103]
	v_mfma_f32_16x16x32_bf16 v[100:103], v[164:167], v[180:183], v[100:103]
	v_mfma_f32_16x16x32_bf16 v[104:107], v[168:171], v[176:179], v[104:107]
	v_mfma_f32_16x16x32_bf16 v[104:107], v[172:175], v[180:183], v[104:107]
	v_mfma_f32_16x16x32_bf16 v[108:111], v[160:163], v[184:187], v[108:111]
	v_mfma_f32_16x16x32_bf16 v[108:111], v[164:167], v[188:191], v[108:111]
	v_mfma_f32_16x16x32_bf16 v[112:115], v[168:171], v[184:187], v[112:115]
	v_mfma_f32_16x16x32_bf16 v[112:115], v[172:175], v[188:191], v[112:115]
	v_mfma_f32_16x16x32_bf16 v[116:119], v[160:163], v[192:195], v[116:119]
	v_mfma_f32_16x16x32_bf16 v[116:119], v[164:167], v[196:199], v[116:119]
	v_mfma_f32_16x16x32_bf16 v[120:123], v[168:171], v[192:195], v[120:123]
	v_mfma_f32_16x16x32_bf16 v[120:123], v[172:175], v[196:199], v[120:123]
	v_mfma_f32_16x16x32_bf16 v[124:127], v[160:163], v[200:203], v[124:127]
	v_mfma_f32_16x16x32_bf16 v[124:127], v[164:167], v[204:207], v[124:127]
	v_mfma_f32_16x16x32_bf16 v[128:131], v[168:171], v[200:203], v[128:131]
	v_mfma_f32_16x16x32_bf16 v[128:131], v[172:175], v[204:207], v[128:131]
	s_setprio 0
	s_barrier
	ds_read_b128 v[144:147], v134
	ds_read_b128 v[148:151], v134 offset:1024
	ds_read_b128 v[152:155], v134 offset:2048
	ds_read_b128 v[156:159], v134 offset:3072
	ds_read_b128 v[160:163], v135
	ds_read_b128 v[164:167], v135 offset:1024
	ds_read_b128 v[168:171], v135 offset:2048
	ds_read_b128 v[172:175], v135 offset:3072
	s_mov_b32 m0, s76
	s_mov_b64 s[8:9], s[64:65]
	ds_read_b128 v[176:179], v141 offset:32768
	ds_read_b128 v[180:183], v141 offset:33792
	ds_read_b128 v[184:187], v141 offset:34816
	ds_read_b128 v[188:191], v141 offset:35840
	ds_read_b128 v[192:195], v141 offset:36864
	ds_read_b128 v[196:199], v141 offset:37888
	ds_read_b128 v[200:203], v141 offset:38912
	ds_read_b128 v[204:207], v141 offset:39936
	s_nop 0
	global_load_lds_dwordx4 v137, s[8:9]
	s_mov_b32 m0, s77
	s_nop 0
	global_load_lds_dwordx4 v136, s[8:9]
	s_add_u32 s8, s64, s20
	s_addc_u32 s9, s65, s21
	s_mov_b32 m0, s78
	s_nop 0
	global_load_lds_dwordx4 v137, s[8:9]
	s_mov_b64 s[100:101], s[8:9]
	s_waitcnt vmcnt(7)
	s_waitcnt lgkmcnt(0)
	s_barrier
	s_setprio 1
	s_waitcnt lgkmcnt(0)
	v_mfma_f32_16x16x32_bf16 v[4:7], v[144:147], v[176:179], v[4:7]
	v_mfma_f32_16x16x32_bf16 v[4:7], v[148:151], v[180:183], v[4:7]
	v_mfma_f32_16x16x32_bf16 v[8:11], v[152:155], v[176:179], v[8:11]
	v_mfma_f32_16x16x32_bf16 v[8:11], v[156:159], v[180:183], v[8:11]
	v_mfma_f32_16x16x32_bf16 v[12:15], v[144:147], v[184:187], v[12:15]
	v_mfma_f32_16x16x32_bf16 v[12:15], v[148:151], v[188:191], v[12:15]
	v_mfma_f32_16x16x32_bf16 v[16:19], v[152:155], v[184:187], v[16:19]
	v_mfma_f32_16x16x32_bf16 v[16:19], v[156:159], v[188:191], v[16:19]
	v_mfma_f32_16x16x32_bf16 v[20:23], v[144:147], v[192:195], v[20:23]
	v_mfma_f32_16x16x32_bf16 v[20:23], v[148:151], v[196:199], v[20:23]
	v_mfma_f32_16x16x32_bf16 v[24:27], v[152:155], v[192:195], v[24:27]
	v_mfma_f32_16x16x32_bf16 v[24:27], v[156:159], v[196:199], v[24:27]
	v_mfma_f32_16x16x32_bf16 v[28:31], v[144:147], v[200:203], v[28:31]
	v_mfma_f32_16x16x32_bf16 v[28:31], v[148:151], v[204:207], v[28:31]
	v_mfma_f32_16x16x32_bf16 v[32:35], v[152:155], v[200:203], v[32:35]
	v_mfma_f32_16x16x32_bf16 v[32:35], v[156:159], v[204:207], v[32:35]
	s_setprio 0
	s_setprio 1
	v_mfma_f32_16x16x32_bf16 v[36:39], v[160:163], v[176:179], v[36:39]
	v_mfma_f32_16x16x32_bf16 v[36:39], v[164:167], v[180:183], v[36:39]
	v_mfma_f32_16x16x32_bf16 v[40:43], v[168:171], v[176:179], v[40:43]
	v_mfma_f32_16x16x32_bf16 v[40:43], v[172:175], v[180:183], v[40:43]
	v_mfma_f32_16x16x32_bf16 v[44:47], v[160:163], v[184:187], v[44:47]
	v_mfma_f32_16x16x32_bf16 v[44:47], v[164:167], v[188:191], v[44:47]
	v_mfma_f32_16x16x32_bf16 v[48:51], v[168:171], v[184:187], v[48:51]
	v_mfma_f32_16x16x32_bf16 v[48:51], v[172:175], v[188:191], v[48:51]
	v_mfma_f32_16x16x32_bf16 v[52:55], v[160:163], v[192:195], v[52:55]
	v_mfma_f32_16x16x32_bf16 v[52:55], v[164:167], v[196:199], v[52:55]
	v_mfma_f32_16x16x32_bf16 v[56:59], v[168:171], v[192:195], v[56:59]
	v_mfma_f32_16x16x32_bf16 v[56:59], v[172:175], v[196:199], v[56:59]
	v_mfma_f32_16x16x32_bf16 v[60:63], v[160:163], v[200:203], v[60:63]
	v_mfma_f32_16x16x32_bf16 v[60:63], v[164:167], v[204:207], v[60:63]
	v_mfma_f32_16x16x32_bf16 v[64:67], v[168:171], v[200:203], v[64:67]
	v_mfma_f32_16x16x32_bf16 v[64:67], v[172:175], v[204:207], v[64:67]
	s_setprio 0
	s_barrier
	s_mov_b32 m0, s79
	s_nop 0
	global_load_lds_dwordx4 v136, s[100:101]
	s_mov_b32 m0, s68
	s_mov_b64 s[8:9], s[18:19]
	ds_read_b128 v[176:179], v141 offset:49152
	ds_read_b128 v[180:183], v141 offset:50176
	ds_read_b128 v[184:187], v141 offset:51200
	ds_read_b128 v[188:191], v141 offset:52224
	ds_read_b128 v[192:195], v141 offset:53248
	ds_read_b128 v[196:199], v141 offset:54272
	ds_read_b128 v[200:203], v141 offset:55296
	ds_read_b128 v[204:207], v141 offset:56320
	s_nop 0
	global_load_lds_dwordx4 v143, s[8:9]
	s_mov_b32 m0, s69
	s_nop 0
	global_load_lds_dwordx4 v142, s[8:9]
	s_add_u32 s8, s18, s20
	s_addc_u32 s9, s19, s21
	s_mov_b32 m0, s91
	s_nop 0
	global_load_lds_dwordx4 v143, s[8:9]
	s_mov_b32 m0, s92
	s_nop 0
	global_load_lds_dwordx4 v142, s[8:9]
	s_waitcnt vmcnt(6)
	s_waitcnt lgkmcnt(0)
	s_barrier
	s_setprio 1
	s_waitcnt lgkmcnt(0)
	v_mfma_f32_16x16x32_bf16 v[68:71], v[144:147], v[176:179], v[68:71]
	v_mfma_f32_16x16x32_bf16 v[68:71], v[148:151], v[180:183], v[68:71]
	v_mfma_f32_16x16x32_bf16 v[72:75], v[152:155], v[176:179], v[72:75]
	v_mfma_f32_16x16x32_bf16 v[72:75], v[156:159], v[180:183], v[72:75]
	v_mfma_f32_16x16x32_bf16 v[76:79], v[144:147], v[184:187], v[76:79]
	v_mfma_f32_16x16x32_bf16 v[76:79], v[148:151], v[188:191], v[76:79]
	v_mfma_f32_16x16x32_bf16 v[80:83], v[152:155], v[184:187], v[80:83]
	v_mfma_f32_16x16x32_bf16 v[80:83], v[156:159], v[188:191], v[80:83]
	v_mfma_f32_16x16x32_bf16 v[84:87], v[144:147], v[192:195], v[84:87]
	v_mfma_f32_16x16x32_bf16 v[84:87], v[148:151], v[196:199], v[84:87]
	v_mfma_f32_16x16x32_bf16 v[88:91], v[152:155], v[192:195], v[88:91]
	v_mfma_f32_16x16x32_bf16 v[88:91], v[156:159], v[196:199], v[88:91]
	v_mfma_f32_16x16x32_bf16 v[92:95], v[144:147], v[200:203], v[92:95]
	v_mfma_f32_16x16x32_bf16 v[92:95], v[148:151], v[204:207], v[92:95]
	v_mfma_f32_16x16x32_bf16 v[96:99], v[152:155], v[200:203], v[96:99]
	v_mfma_f32_16x16x32_bf16 v[96:99], v[156:159], v[204:207], v[96:99]
	s_setprio 0
	s_setprio 1
	v_mfma_f32_16x16x32_bf16 v[100:103], v[160:163], v[176:179], v[100:103]
	v_mfma_f32_16x16x32_bf16 v[100:103], v[164:167], v[180:183], v[100:103]
	v_mfma_f32_16x16x32_bf16 v[104:107], v[168:171], v[176:179], v[104:107]
	v_mfma_f32_16x16x32_bf16 v[104:107], v[172:175], v[180:183], v[104:107]
	v_mfma_f32_16x16x32_bf16 v[108:111], v[160:163], v[184:187], v[108:111]
	v_mfma_f32_16x16x32_bf16 v[108:111], v[164:167], v[188:191], v[108:111]
	v_mfma_f32_16x16x32_bf16 v[112:115], v[168:171], v[184:187], v[112:115]
	v_mfma_f32_16x16x32_bf16 v[112:115], v[172:175], v[188:191], v[112:115]
	v_mfma_f32_16x16x32_bf16 v[116:119], v[160:163], v[192:195], v[116:119]
	v_mfma_f32_16x16x32_bf16 v[116:119], v[164:167], v[196:199], v[116:119]
	v_mfma_f32_16x16x32_bf16 v[120:123], v[168:171], v[192:195], v[120:123]
	v_mfma_f32_16x16x32_bf16 v[120:123], v[172:175], v[196:199], v[120:123]
	v_mfma_f32_16x16x32_bf16 v[124:127], v[160:163], v[200:203], v[124:127]
	v_mfma_f32_16x16x32_bf16 v[124:127], v[164:167], v[204:207], v[124:127]
	v_mfma_f32_16x16x32_bf16 v[128:131], v[168:171], v[200:203], v[128:131]
	v_mfma_f32_16x16x32_bf16 v[128:131], v[172:175], v[204:207], v[128:131]
	s_setprio 0
	s_barrier
	s_add_i32 s8, s95, 2
	s_add_u32 s93, s93, 0x100
	s_addc_u32 s94, s94, 0
	s_add_u32 s66, s66, 0x100
	s_addc_u32 s67, s67, 0
	s_cmp_ge_i32 s95, s72
	s_mov_b32 s95, s8
	s_cbranch_scc0 .LBB0_1042
	v_readlane_b32 s94, v255, 39
	v_readlane_b32 s95, v255, 40
	s_branch .LBB0_1031

.LBB0_1156:
	ds_read_b128 v[136:139], v132
	ds_read_b128 v[140:143], v132 offset:1024
	ds_read_b128 v[144:147], v132 offset:2048
	ds_read_b128 v[148:151], v132 offset:3072
	ds_read_b128 v[152:155], v133
	ds_read_b128 v[156:159], v133 offset:1024
	ds_read_b128 v[160:163], v133 offset:2048
	ds_read_b128 v[164:167], v133 offset:3072
	s_cmp_eq_u32 s6, s82
	s_cselect_b32 s17, s27, s81
	s_cselect_b32 s16, s26, s80
	s_cselect_b32 s21, s51, s53
	s_cselect_b32 s20, s50, s52
	s_add_u32 s8, s52, 0xffffff80
	s_addc_u32 s9, s53, -1
	s_mov_b32 m0, s66
	s_mov_b64 s[18:19], s[8:9]
	ds_read_b128 v[168:171], v244 offset:8192
	ds_read_b128 v[172:175], v244 offset:9216
	ds_read_b128 v[176:179], v244 offset:10240
	ds_read_b128 v[180:183], v244 offset:11264
	ds_read_b128 v[184:187], v244 offset:12288
	ds_read_b128 v[188:191], v244 offset:13312
	ds_read_b128 v[192:195], v244 offset:14336
	ds_read_b128 v[196:199], v244 offset:15360
	s_add_u32 s8, s8, s28
	global_load_lds_dwordx4 v238, s[18:19]
	s_mov_b32 m0, s67
	s_addc_u32 s9, s9, s29
	global_load_lds_dwordx4 v2, s[18:19]
	s_mov_b32 m0, s68
	s_add_u32 s18, s16, 0x80
	global_load_lds_dwordx4 v238, s[8:9]
	s_addc_u32 s19, s17, 0
	s_mov_b64 s[100:101], s[8:9]
	s_waitcnt vmcnt(7)
	s_waitcnt lgkmcnt(0)
	s_barrier
	s_setprio 1
	s_waitcnt lgkmcnt(0)
	v_mfma_f32_16x16x32_bf16 v[4:7], v[136:139], v[168:171], v[4:7]
	v_mfma_f32_16x16x32_bf16 v[4:7], v[140:143], v[172:175], v[4:7]
	v_mfma_f32_16x16x32_bf16 v[8:11], v[144:147], v[168:171], v[8:11]
	v_mfma_f32_16x16x32_bf16 v[8:11], v[148:151], v[172:175], v[8:11]
	v_mfma_f32_16x16x32_bf16 v[12:15], v[136:139], v[176:179], v[12:15]
	v_mfma_f32_16x16x32_bf16 v[12:15], v[140:143], v[180:183], v[12:15]
	v_mfma_f32_16x16x32_bf16 v[16:19], v[144:147], v[176:179], v[16:19]
	v_mfma_f32_16x16x32_bf16 v[16:19], v[148:151], v[180:183], v[16:19]
	v_mfma_f32_16x16x32_bf16 v[20:23], v[136:139], v[184:187], v[20:23]
	v_mfma_f32_16x16x32_bf16 v[20:23], v[140:143], v[188:191], v[20:23]
	v_mfma_f32_16x16x32_bf16 v[24:27], v[144:147], v[184:187], v[24:27]
	v_mfma_f32_16x16x32_bf16 v[24:27], v[148:151], v[188:191], v[24:27]
	v_mfma_f32_16x16x32_bf16 v[28:31], v[136:139], v[192:195], v[28:31]
	v_mfma_f32_16x16x32_bf16 v[28:31], v[140:143], v[196:199], v[28:31]
	v_mfma_f32_16x16x32_bf16 v[32:35], v[144:147], v[192:195], v[32:35]
	v_mfma_f32_16x16x32_bf16 v[32:35], v[148:151], v[196:199], v[32:35]
	s_setprio 0
	s_setprio 1
	v_mfma_f32_16x16x32_bf16 v[36:39], v[152:155], v[168:171], v[36:39]
	v_mfma_f32_16x16x32_bf16 v[36:39], v[156:159], v[172:175], v[36:39]
	v_mfma_f32_16x16x32_bf16 v[40:43], v[160:163], v[168:171], v[40:43]
	v_mfma_f32_16x16x32_bf16 v[40:43], v[164:167], v[172:175], v[40:43]
	v_mfma_f32_16x16x32_bf16 v[44:47], v[152:155], v[176:179], v[44:47]
	v_mfma_f32_16x16x32_bf16 v[44:47], v[156:159], v[180:183], v[44:47]
	v_mfma_f32_16x16x32_bf16 v[48:51], v[160:163], v[176:179], v[48:51]
	v_mfma_f32_16x16x32_bf16 v[48:51], v[164:167], v[180:183], v[48:51]
	v_mfma_f32_16x16x32_bf16 v[52:55], v[152:155], v[184:187], v[52:55]
	v_mfma_f32_16x16x32_bf16 v[52:55], v[156:159], v[188:191], v[52:55]
	v_mfma_f32_16x16x32_bf16 v[56:59], v[160:163], v[184:187], v[56:59]
	v_mfma_f32_16x16x32_bf16 v[56:59], v[164:167], v[188:191], v[56:59]
	v_mfma_f32_16x16x32_bf16 v[60:63], v[152:155], v[192:195], v[60:63]
	v_mfma_f32_16x16x32_bf16 v[60:63], v[156:159], v[196:199], v[60:63]
	v_mfma_f32_16x16x32_bf16 v[64:67], v[160:163], v[192:195], v[64:67]
	v_mfma_f32_16x16x32_bf16 v[64:67], v[164:167], v[196:199], v[64:67]
	s_setprio 0
	s_barrier
	s_mov_b32 m0, s69
	s_nop 0
	global_load_lds_dwordx4 v2, s[100:101]
	s_mov_b32 m0, s72
	s_mov_b64 s[8:9], s[16:17]
	ds_read_b128 v[168:171], v244 offset:24576
	ds_read_b128 v[172:175], v244 offset:25600
	ds_read_b128 v[176:179], v244 offset:26624
	ds_read_b128 v[180:183], v244 offset:27648
	ds_read_b128 v[184:187], v244 offset:28672
	ds_read_b128 v[188:191], v244 offset:29696
	ds_read_b128 v[192:195], v244 offset:30720
	ds_read_b128 v[196:199], v244 offset:31744
	s_nop 0
	global_load_lds_dwordx4 v246, s[8:9]
	s_mov_b32 m0, s73
	s_nop 0
	global_load_lds_dwordx4 v245, s[8:9]
	s_add_u32 s8, s16, s28
	s_addc_u32 s9, s17, s29
	s_mov_b32 m0, s76
	s_nop 0
	global_load_lds_dwordx4 v246, s[8:9]
	s_mov_b32 m0, s77
	s_nop 0
	global_load_lds_dwordx4 v245, s[8:9]
	s_waitcnt vmcnt(6)
	s_waitcnt lgkmcnt(0)
	s_barrier
	s_setprio 1
	s_waitcnt lgkmcnt(0)
	v_mfma_f32_16x16x32_bf16 v[68:71], v[136:139], v[168:171], v[68:71]
	v_mfma_f32_16x16x32_bf16 v[68:71], v[140:143], v[172:175], v[68:71]
	v_mfma_f32_16x16x32_bf16 v[72:75], v[144:147], v[168:171], v[72:75]
	v_mfma_f32_16x16x32_bf16 v[72:75], v[148:151], v[172:175], v[72:75]
	v_mfma_f32_16x16x32_bf16 v[76:79], v[136:139], v[176:179], v[76:79]
	v_mfma_f32_16x16x32_bf16 v[76:79], v[140:143], v[180:183], v[76:79]
	v_mfma_f32_16x16x32_bf16 v[80:83], v[144:147], v[176:179], v[80:83]
	v_mfma_f32_16x16x32_bf16 v[80:83], v[148:151], v[180:183], v[80:83]
	v_mfma_f32_16x16x32_bf16 v[84:87], v[136:139], v[184:187], v[84:87]
	v_mfma_f32_16x16x32_bf16 v[84:87], v[140:143], v[188:191], v[84:87]
	v_mfma_f32_16x16x32_bf16 v[88:91], v[144:147], v[184:187], v[88:91]
	v_mfma_f32_16x16x32_bf16 v[88:91], v[148:151], v[188:191], v[88:91]
	v_mfma_f32_16x16x32_bf16 v[92:95], v[136:139], v[192:195], v[92:95]
	v_mfma_f32_16x16x32_bf16 v[92:95], v[140:143], v[196:199], v[92:95]
	v_mfma_f32_16x16x32_bf16 v[96:99], v[144:147], v[192:195], v[96:99]
	v_mfma_f32_16x16x32_bf16 v[96:99], v[148:151], v[196:199], v[96:99]
	s_setprio 0
	s_setprio 1
	v_mfma_f32_16x16x32_bf16 v[100:103], v[152:155], v[168:171], v[100:103]
	v_mfma_f32_16x16x32_bf16 v[100:103], v[156:159], v[172:175], v[100:103]
	v_mfma_f32_16x16x32_bf16 v[104:107], v[160:163], v[168:171], v[104:107]
	v_mfma_f32_16x16x32_bf16 v[104:107], v[164:167], v[172:175], v[104:107]
	v_mfma_f32_16x16x32_bf16 v[108:111], v[152:155], v[176:179], v[108:111]
	v_mfma_f32_16x16x32_bf16 v[108:111], v[156:159], v[180:183], v[108:111]
	v_mfma_f32_16x16x32_bf16 v[112:115], v[160:163], v[176:179], v[112:115]
	v_mfma_f32_16x16x32_bf16 v[112:115], v[164:167], v[180:183], v[112:115]
	v_mfma_f32_16x16x32_bf16 v[116:119], v[152:155], v[184:187], v[116:119]
	v_mfma_f32_16x16x32_bf16 v[116:119], v[156:159], v[188:191], v[116:119]
	v_mfma_f32_16x16x32_bf16 v[120:123], v[160:163], v[184:187], v[120:123]
	v_mfma_f32_16x16x32_bf16 v[120:123], v[164:167], v[188:191], v[120:123]
	v_mfma_f32_16x16x32_bf16 v[124:127], v[152:155], v[192:195], v[124:127]
	v_mfma_f32_16x16x32_bf16 v[124:127], v[156:159], v[196:199], v[124:127]
	v_mfma_f32_16x16x32_bf16 v[128:131], v[160:163], v[192:195], v[128:131]
	v_mfma_f32_16x16x32_bf16 v[128:131], v[164:167], v[196:199], v[128:131]
	s_setprio 0
	s_barrier
	ds_read_b128 v[136:139], v134
	ds_read_b128 v[140:143], v134 offset:1024
	ds_read_b128 v[144:147], v134 offset:2048
	ds_read_b128 v[148:151], v134 offset:3072
	ds_read_b128 v[152:155], v135
	ds_read_b128 v[156:159], v135 offset:1024
	ds_read_b128 v[160:163], v135 offset:2048
	ds_read_b128 v[164:167], v135 offset:3072
	s_mov_b32 m0, s58
	s_mov_b64 s[8:9], s[20:21]
	ds_read_b128 v[168:171], v244 offset:40960
	ds_read_b128 v[172:175], v244 offset:41984
	ds_read_b128 v[176:179], v244 offset:43008
	ds_read_b128 v[180:183], v244 offset:44032
	ds_read_b128 v[184:187], v244 offset:45056
	ds_read_b128 v[188:191], v244 offset:46080
	ds_read_b128 v[192:195], v244 offset:47104
	ds_read_b128 v[196:199], v244 offset:48128
	s_nop 0
	global_load_lds_dwordx4 v238, s[8:9]
	s_mov_b32 m0, s59
	s_nop 0
	global_load_lds_dwordx4 v2, s[8:9]
	s_add_u32 s8, s20, s28
	s_addc_u32 s9, s21, s29
	s_mov_b32 m0, s60
	s_nop 0
	global_load_lds_dwordx4 v238, s[8:9]
	s_mov_b64 s[100:101], s[8:9]
	s_waitcnt vmcnt(7)
	s_waitcnt lgkmcnt(0)
	s_barrier
	s_setprio 1
	s_waitcnt lgkmcnt(0)
	v_mfma_f32_16x16x32_bf16 v[4:7], v[136:139], v[168:171], v[4:7]
	v_mfma_f32_16x16x32_bf16 v[4:7], v[140:143], v[172:175], v[4:7]
	v_mfma_f32_16x16x32_bf16 v[8:11], v[144:147], v[168:171], v[8:11]
	v_mfma_f32_16x16x32_bf16 v[8:11], v[148:151], v[172:175], v[8:11]
	v_mfma_f32_16x16x32_bf16 v[12:15], v[136:139], v[176:179], v[12:15]
	v_mfma_f32_16x16x32_bf16 v[12:15], v[140:143], v[180:183], v[12:15]
	v_mfma_f32_16x16x32_bf16 v[16:19], v[144:147], v[176:179], v[16:19]
	v_mfma_f32_16x16x32_bf16 v[16:19], v[148:151], v[180:183], v[16:19]
	v_mfma_f32_16x16x32_bf16 v[20:23], v[136:139], v[184:187], v[20:23]
	v_mfma_f32_16x16x32_bf16 v[20:23], v[140:143], v[188:191], v[20:23]
	v_mfma_f32_16x16x32_bf16 v[24:27], v[144:147], v[184:187], v[24:27]
	v_mfma_f32_16x16x32_bf16 v[24:27], v[148:151], v[188:191], v[24:27]
	v_mfma_f32_16x16x32_bf16 v[28:31], v[136:139], v[192:195], v[28:31]
	v_mfma_f32_16x16x32_bf16 v[28:31], v[140:143], v[196:199], v[28:31]
	v_mfma_f32_16x16x32_bf16 v[32:35], v[144:147], v[192:195], v[32:35]
	v_mfma_f32_16x16x32_bf16 v[32:35], v[148:151], v[196:199], v[32:35]
	s_setprio 0
	s_setprio 1
	v_mfma_f32_16x16x32_bf16 v[36:39], v[152:155], v[168:171], v[36:39]
	v_mfma_f32_16x16x32_bf16 v[36:39], v[156:159], v[172:175], v[36:39]
	v_mfma_f32_16x16x32_bf16 v[40:43], v[160:163], v[168:171], v[40:43]
	v_mfma_f32_16x16x32_bf16 v[40:43], v[164:167], v[172:175], v[40:43]
	v_mfma_f32_16x16x32_bf16 v[44:47], v[152:155], v[176:179], v[44:47]
	v_mfma_f32_16x16x32_bf16 v[44:47], v[156:159], v[180:183], v[44:47]
	v_mfma_f32_16x16x32_bf16 v[48:51], v[160:163], v[176:179], v[48:51]
	v_mfma_f32_16x16x32_bf16 v[48:51], v[164:167], v[180:183], v[48:51]
	v_mfma_f32_16x16x32_bf16 v[52:55], v[152:155], v[184:187], v[52:55]
	v_mfma_f32_16x16x32_bf16 v[52:55], v[156:159], v[188:191], v[52:55]
	v_mfma_f32_16x16x32_bf16 v[56:59], v[160:163], v[184:187], v[56:59]
	v_mfma_f32_16x16x32_bf16 v[56:59], v[164:167], v[188:191], v[56:59]
	v_mfma_f32_16x16x32_bf16 v[60:63], v[152:155], v[192:195], v[60:63]
	v_mfma_f32_16x16x32_bf16 v[60:63], v[156:159], v[196:199], v[60:63]
	v_mfma_f32_16x16x32_bf16 v[64:67], v[160:163], v[192:195], v[64:67]
	v_mfma_f32_16x16x32_bf16 v[64:67], v[164:167], v[196:199], v[64:67]
	s_setprio 0
	s_barrier
	s_mov_b32 m0, s61
	s_nop 0
	global_load_lds_dwordx4 v2, s[100:101]
	s_mov_b32 m0, s42
	s_mov_b64 s[8:9], s[18:19]
	ds_read_b128 v[168:171], v244 offset:57344
	ds_read_b128 v[172:175], v244 offset:58368
	ds_read_b128 v[176:179], v244 offset:59392
	ds_read_b128 v[180:183], v244 offset:60416
	ds_read_b128 v[184:187], v244 offset:61440
	ds_read_b128 v[188:191], v244 offset:62464
	ds_read_b128 v[192:195], v244 offset:63488
	ds_read_b128 v[196:199], v244 offset:64512
	s_nop 0
	global_load_lds_dwordx4 v246, s[8:9]
	s_mov_b32 m0, s43
	s_nop 0
	global_load_lds_dwordx4 v245, s[8:9]
	s_add_u32 s8, s18, s28
	s_addc_u32 s9, s19, s29
	s_mov_b32 m0, s78
	s_nop 0
	global_load_lds_dwordx4 v246, s[8:9]
	s_mov_b32 m0, s79
	s_nop 0
	global_load_lds_dwordx4 v245, s[8:9]
	s_waitcnt vmcnt(6)
	s_waitcnt lgkmcnt(0)
	s_barrier
	s_setprio 1
	s_waitcnt lgkmcnt(0)
	v_mfma_f32_16x16x32_bf16 v[68:71], v[136:139], v[168:171], v[68:71]
	v_mfma_f32_16x16x32_bf16 v[68:71], v[140:143], v[172:175], v[68:71]
	v_mfma_f32_16x16x32_bf16 v[72:75], v[144:147], v[168:171], v[72:75]
	v_mfma_f32_16x16x32_bf16 v[72:75], v[148:151], v[172:175], v[72:75]
	v_mfma_f32_16x16x32_bf16 v[76:79], v[136:139], v[176:179], v[76:79]
	v_mfma_f32_16x16x32_bf16 v[76:79], v[140:143], v[180:183], v[76:79]
	v_mfma_f32_16x16x32_bf16 v[80:83], v[144:147], v[176:179], v[80:83]
	v_mfma_f32_16x16x32_bf16 v[80:83], v[148:151], v[180:183], v[80:83]
	v_mfma_f32_16x16x32_bf16 v[84:87], v[136:139], v[184:187], v[84:87]
	v_mfma_f32_16x16x32_bf16 v[84:87], v[140:143], v[188:191], v[84:87]
	v_mfma_f32_16x16x32_bf16 v[88:91], v[144:147], v[184:187], v[88:91]
	v_mfma_f32_16x16x32_bf16 v[88:91], v[148:151], v[188:191], v[88:91]
	v_mfma_f32_16x16x32_bf16 v[92:95], v[136:139], v[192:195], v[92:95]
	v_mfma_f32_16x16x32_bf16 v[92:95], v[140:143], v[196:199], v[92:95]
	v_mfma_f32_16x16x32_bf16 v[96:99], v[144:147], v[192:195], v[96:99]
	v_mfma_f32_16x16x32_bf16 v[96:99], v[148:151], v[196:199], v[96:99]
	s_setprio 0
	s_setprio 1
	v_mfma_f32_16x16x32_bf16 v[100:103], v[152:155], v[168:171], v[100:103]
	v_mfma_f32_16x16x32_bf16 v[100:103], v[156:159], v[172:175], v[100:103]
	v_mfma_f32_16x16x32_bf16 v[104:107], v[160:163], v[168:171], v[104:107]
	v_mfma_f32_16x16x32_bf16 v[104:107], v[164:167], v[172:175], v[104:107]
	v_mfma_f32_16x16x32_bf16 v[108:111], v[152:155], v[176:179], v[108:111]
	v_mfma_f32_16x16x32_bf16 v[108:111], v[156:159], v[180:183], v[108:111]
	v_mfma_f32_16x16x32_bf16 v[112:115], v[160:163], v[176:179], v[112:115]
	v_mfma_f32_16x16x32_bf16 v[112:115], v[164:167], v[180:183], v[112:115]
	v_mfma_f32_16x16x32_bf16 v[116:119], v[152:155], v[184:187], v[116:119]
	v_mfma_f32_16x16x32_bf16 v[116:119], v[156:159], v[188:191], v[116:119]
	v_mfma_f32_16x16x32_bf16 v[120:123], v[160:163], v[184:187], v[120:123]
	v_mfma_f32_16x16x32_bf16 v[120:123], v[164:167], v[188:191], v[120:123]
	v_mfma_f32_16x16x32_bf16 v[124:127], v[152:155], v[192:195], v[124:127]
	v_mfma_f32_16x16x32_bf16 v[124:127], v[156:159], v[196:199], v[124:127]
	v_mfma_f32_16x16x32_bf16 v[128:131], v[160:163], v[192:195], v[128:131]
	v_mfma_f32_16x16x32_bf16 v[128:131], v[164:167], v[196:199], v[128:131]
	s_setprio 0
	s_barrier
	s_add_i32 s8, s82, 2
	s_add_u32 s80, s80, 0x100
	s_addc_u32 s81, s81, 0
	s_add_u32 s52, s52, 0x100
	s_addc_u32 s53, s53, 0
	s_cmp_ge_i32 s82, s6
	s_mov_b32 s82, s8
	s_cbranch_scc0 .LBB0_1156

.LBB0_1176:
	ds_read_b128 v[136:139], v132
	ds_read_b128 v[140:143], v132 offset:1024
	ds_read_b128 v[144:147], v132 offset:2048
	ds_read_b128 v[148:151], v132 offset:3072
	ds_read_b128 v[152:155], v133
	ds_read_b128 v[156:159], v133 offset:1024
	ds_read_b128 v[160:163], v133 offset:2048
	ds_read_b128 v[164:167], v133 offset:3072
	s_cmp_eq_u32 s6, s80
	s_cselect_b32 s17, s21, s79
	s_cselect_b32 s16, s20, s78
	s_cselect_b32 s27, s41, s51
	s_cselect_b32 s26, s40, s50
	s_add_u32 s8, s50, 0xffffff80
	s_addc_u32 s9, s51, -1
	s_mov_b32 m0, s64
	s_mov_b64 s[18:19], s[8:9]
	ds_read_b128 v[168:171], v244
	ds_read_b128 v[172:175], v244 offset:1024
	ds_read_b128 v[176:179], v244 offset:2048
	ds_read_b128 v[180:183], v244 offset:3072
	ds_read_b128 v[184:187], v244 offset:4096
	ds_read_b128 v[188:191], v244 offset:5120
	ds_read_b128 v[192:195], v244 offset:6144
	ds_read_b128 v[196:199], v244 offset:7168
	s_add_u32 s8, s8, s28
	global_load_lds_dwordx4 v238, s[18:19]
	s_mov_b32 m0, s65
	s_addc_u32 s9, s9, s29
	global_load_lds_dwordx4 v2, s[18:19]
	s_mov_b32 m0, s66
	s_add_u32 s18, s16, 0x80
	global_load_lds_dwordx4 v238, s[8:9]
	s_addc_u32 s19, s17, 0
	s_mov_b64 s[100:101], s[8:9]
	s_waitcnt vmcnt(7)
	s_waitcnt lgkmcnt(0)
	s_barrier
	s_setprio 1
	s_waitcnt lgkmcnt(0)
	v_mfma_f32_16x16x32_bf16 v[4:7], v[136:139], v[168:171], v[4:7]
	v_mfma_f32_16x16x32_bf16 v[4:7], v[140:143], v[172:175], v[4:7]
	v_mfma_f32_16x16x32_bf16 v[8:11], v[144:147], v[168:171], v[8:11]
	v_mfma_f32_16x16x32_bf16 v[8:11], v[148:151], v[172:175], v[8:11]
	v_mfma_f32_16x16x32_bf16 v[12:15], v[136:139], v[176:179], v[12:15]
	v_mfma_f32_16x16x32_bf16 v[12:15], v[140:143], v[180:183], v[12:15]
	v_mfma_f32_16x16x32_bf16 v[16:19], v[144:147], v[176:179], v[16:19]
	v_mfma_f32_16x16x32_bf16 v[16:19], v[148:151], v[180:183], v[16:19]
	v_mfma_f32_16x16x32_bf16 v[20:23], v[136:139], v[184:187], v[20:23]
	v_mfma_f32_16x16x32_bf16 v[20:23], v[140:143], v[188:191], v[20:23]
	v_mfma_f32_16x16x32_bf16 v[24:27], v[144:147], v[184:187], v[24:27]
	v_mfma_f32_16x16x32_bf16 v[24:27], v[148:151], v[188:191], v[24:27]
	v_mfma_f32_16x16x32_bf16 v[28:31], v[136:139], v[192:195], v[28:31]
	v_mfma_f32_16x16x32_bf16 v[28:31], v[140:143], v[196:199], v[28:31]
	v_mfma_f32_16x16x32_bf16 v[32:35], v[144:147], v[192:195], v[32:35]
	v_mfma_f32_16x16x32_bf16 v[32:35], v[148:151], v[196:199], v[32:35]
	s_setprio 0
	s_setprio 1
	v_mfma_f32_16x16x32_bf16 v[36:39], v[152:155], v[168:171], v[36:39]
	v_mfma_f32_16x16x32_bf16 v[36:39], v[156:159], v[172:175], v[36:39]
	v_mfma_f32_16x16x32_bf16 v[40:43], v[160:163], v[168:171], v[40:43]
	v_mfma_f32_16x16x32_bf16 v[40:43], v[164:167], v[172:175], v[40:43]
	v_mfma_f32_16x16x32_bf16 v[44:47], v[152:155], v[176:179], v[44:47]
	v_mfma_f32_16x16x32_bf16 v[44:47], v[156:159], v[180:183], v[44:47]
	v_mfma_f32_16x16x32_bf16 v[48:51], v[160:163], v[176:179], v[48:51]
	v_mfma_f32_16x16x32_bf16 v[48:51], v[164:167], v[180:183], v[48:51]
	v_mfma_f32_16x16x32_bf16 v[52:55], v[152:155], v[184:187], v[52:55]
	v_mfma_f32_16x16x32_bf16 v[52:55], v[156:159], v[188:191], v[52:55]
	v_mfma_f32_16x16x32_bf16 v[56:59], v[160:163], v[184:187], v[56:59]
	v_mfma_f32_16x16x32_bf16 v[56:59], v[164:167], v[188:191], v[56:59]
	v_mfma_f32_16x16x32_bf16 v[60:63], v[152:155], v[192:195], v[60:63]
	v_mfma_f32_16x16x32_bf16 v[60:63], v[156:159], v[196:199], v[60:63]
	v_mfma_f32_16x16x32_bf16 v[64:67], v[160:163], v[192:195], v[64:67]
	v_mfma_f32_16x16x32_bf16 v[64:67], v[164:167], v[196:199], v[64:67]
	s_setprio 0
	s_barrier
	s_mov_b32 m0, s67
	s_nop 0
	global_load_lds_dwordx4 v2, s[100:101]
	s_mov_b32 m0, s68
	s_mov_b64 s[8:9], s[16:17]
	ds_read_b128 v[168:171], v244 offset:16384
	ds_read_b128 v[172:175], v244 offset:17408
	ds_read_b128 v[176:179], v244 offset:18432
	ds_read_b128 v[180:183], v244 offset:19456
	ds_read_b128 v[184:187], v244 offset:20480
	ds_read_b128 v[188:191], v244 offset:21504
	ds_read_b128 v[192:195], v244 offset:22528
	ds_read_b128 v[196:199], v244 offset:23552
	s_nop 0
	global_load_lds_dwordx4 v246, s[8:9]
	s_mov_b32 m0, s69
	s_nop 0
	global_load_lds_dwordx4 v245, s[8:9]
	s_add_u32 s8, s16, s28
	s_addc_u32 s9, s17, s29
	s_mov_b32 m0, s72
	s_nop 0
	global_load_lds_dwordx4 v246, s[8:9]
	s_mov_b32 m0, s73
	s_nop 0
	global_load_lds_dwordx4 v245, s[8:9]
	s_waitcnt vmcnt(6)
	s_waitcnt lgkmcnt(0)
	s_barrier
	s_setprio 1
	s_waitcnt lgkmcnt(0)
	v_mfma_f32_16x16x32_bf16 v[68:71], v[136:139], v[168:171], v[68:71]
	v_mfma_f32_16x16x32_bf16 v[68:71], v[140:143], v[172:175], v[68:71]
	v_mfma_f32_16x16x32_bf16 v[72:75], v[144:147], v[168:171], v[72:75]
	v_mfma_f32_16x16x32_bf16 v[72:75], v[148:151], v[172:175], v[72:75]
	v_mfma_f32_16x16x32_bf16 v[76:79], v[136:139], v[176:179], v[76:79]
	v_mfma_f32_16x16x32_bf16 v[76:79], v[140:143], v[180:183], v[76:79]
	v_mfma_f32_16x16x32_bf16 v[80:83], v[144:147], v[176:179], v[80:83]
	v_mfma_f32_16x16x32_bf16 v[80:83], v[148:151], v[180:183], v[80:83]
	v_mfma_f32_16x16x32_bf16 v[84:87], v[136:139], v[184:187], v[84:87]
	v_mfma_f32_16x16x32_bf16 v[84:87], v[140:143], v[188:191], v[84:87]
	v_mfma_f32_16x16x32_bf16 v[88:91], v[144:147], v[184:187], v[88:91]
	v_mfma_f32_16x16x32_bf16 v[88:91], v[148:151], v[188:191], v[88:91]
	v_mfma_f32_16x16x32_bf16 v[92:95], v[136:139], v[192:195], v[92:95]
	v_mfma_f32_16x16x32_bf16 v[92:95], v[140:143], v[196:199], v[92:95]
	v_mfma_f32_16x16x32_bf16 v[96:99], v[144:147], v[192:195], v[96:99]
	v_mfma_f32_16x16x32_bf16 v[96:99], v[148:151], v[196:199], v[96:99]
	s_setprio 0
	s_setprio 1
	v_mfma_f32_16x16x32_bf16 v[100:103], v[152:155], v[168:171], v[100:103]
	v_mfma_f32_16x16x32_bf16 v[100:103], v[156:159], v[172:175], v[100:103]
	v_mfma_f32_16x16x32_bf16 v[104:107], v[160:163], v[168:171], v[104:107]
	v_mfma_f32_16x16x32_bf16 v[104:107], v[164:167], v[172:175], v[104:107]
	v_mfma_f32_16x16x32_bf16 v[108:111], v[152:155], v[176:179], v[108:111]
	v_mfma_f32_16x16x32_bf16 v[108:111], v[156:159], v[180:183], v[108:111]
	v_mfma_f32_16x16x32_bf16 v[112:115], v[160:163], v[176:179], v[112:115]
	v_mfma_f32_16x16x32_bf16 v[112:115], v[164:167], v[180:183], v[112:115]
	v_mfma_f32_16x16x32_bf16 v[116:119], v[152:155], v[184:187], v[116:119]
	v_mfma_f32_16x16x32_bf16 v[116:119], v[156:159], v[188:191], v[116:119]
	v_mfma_f32_16x16x32_bf16 v[120:123], v[160:163], v[184:187], v[120:123]
	v_mfma_f32_16x16x32_bf16 v[120:123], v[164:167], v[188:191], v[120:123]
	v_mfma_f32_16x16x32_bf16 v[124:127], v[152:155], v[192:195], v[124:127]
	v_mfma_f32_16x16x32_bf16 v[124:127], v[156:159], v[196:199], v[124:127]
	v_mfma_f32_16x16x32_bf16 v[128:131], v[160:163], v[192:195], v[128:131]
	v_mfma_f32_16x16x32_bf16 v[128:131], v[164:167], v[196:199], v[128:131]
	s_setprio 0
	s_barrier
	ds_read_b128 v[136:139], v134
	ds_read_b128 v[140:143], v134 offset:1024
	ds_read_b128 v[144:147], v134 offset:2048
	ds_read_b128 v[148:151], v134 offset:3072
	ds_read_b128 v[152:155], v135
	ds_read_b128 v[156:159], v135 offset:1024
	ds_read_b128 v[160:163], v135 offset:2048
	ds_read_b128 v[164:167], v135 offset:3072
	s_mov_b32 m0, s53
	s_mov_b64 s[8:9], s[26:27]
	ds_read_b128 v[168:171], v244 offset:32768
	ds_read_b128 v[172:175], v244 offset:33792
	ds_read_b128 v[176:179], v244 offset:34816
	ds_read_b128 v[180:183], v244 offset:35840
	ds_read_b128 v[184:187], v244 offset:36864
	ds_read_b128 v[188:191], v244 offset:37888
	ds_read_b128 v[192:195], v244 offset:38912
	ds_read_b128 v[196:199], v244 offset:39936
	s_nop 0
	global_load_lds_dwordx4 v238, s[8:9]
	s_mov_b32 m0, s57
	s_nop 0
	global_load_lds_dwordx4 v2, s[8:9]
	s_add_u32 s8, s26, s28
	s_addc_u32 s9, s27, s29
	s_mov_b32 m0, s58
	s_nop 0
	global_load_lds_dwordx4 v238, s[8:9]
	s_mov_b64 s[100:101], s[8:9]
	s_waitcnt vmcnt(7)
	s_waitcnt lgkmcnt(0)
	s_barrier
	s_setprio 1
	s_waitcnt lgkmcnt(0)
	v_mfma_f32_16x16x32_bf16 v[4:7], v[136:139], v[168:171], v[4:7]
	v_mfma_f32_16x16x32_bf16 v[4:7], v[140:143], v[172:175], v[4:7]
	v_mfma_f32_16x16x32_bf16 v[8:11], v[144:147], v[168:171], v[8:11]
	v_mfma_f32_16x16x32_bf16 v[8:11], v[148:151], v[172:175], v[8:11]
	v_mfma_f32_16x16x32_bf16 v[12:15], v[136:139], v[176:179], v[12:15]
	v_mfma_f32_16x16x32_bf16 v[12:15], v[140:143], v[180:183], v[12:15]
	v_mfma_f32_16x16x32_bf16 v[16:19], v[144:147], v[176:179], v[16:19]
	v_mfma_f32_16x16x32_bf16 v[16:19], v[148:151], v[180:183], v[16:19]
	v_mfma_f32_16x16x32_bf16 v[20:23], v[136:139], v[184:187], v[20:23]
	v_mfma_f32_16x16x32_bf16 v[20:23], v[140:143], v[188:191], v[20:23]
	v_mfma_f32_16x16x32_bf16 v[24:27], v[144:147], v[184:187], v[24:27]
	v_mfma_f32_16x16x32_bf16 v[24:27], v[148:151], v[188:191], v[24:27]
	v_mfma_f32_16x16x32_bf16 v[28:31], v[136:139], v[192:195], v[28:31]
	v_mfma_f32_16x16x32_bf16 v[28:31], v[140:143], v[196:199], v[28:31]
	v_mfma_f32_16x16x32_bf16 v[32:35], v[144:147], v[192:195], v[32:35]
	v_mfma_f32_16x16x32_bf16 v[32:35], v[148:151], v[196:199], v[32:35]
	s_setprio 0
	s_setprio 1
	v_mfma_f32_16x16x32_bf16 v[36:39], v[152:155], v[168:171], v[36:39]
	v_mfma_f32_16x16x32_bf16 v[36:39], v[156:159], v[172:175], v[36:39]
	v_mfma_f32_16x16x32_bf16 v[40:43], v[160:163], v[168:171], v[40:43]
	v_mfma_f32_16x16x32_bf16 v[40:43], v[164:167], v[172:175], v[40:43]
	v_mfma_f32_16x16x32_bf16 v[44:47], v[152:155], v[176:179], v[44:47]
	v_mfma_f32_16x16x32_bf16 v[44:47], v[156:159], v[180:183], v[44:47]
	v_mfma_f32_16x16x32_bf16 v[48:51], v[160:163], v[176:179], v[48:51]
	v_mfma_f32_16x16x32_bf16 v[48:51], v[164:167], v[180:183], v[48:51]
	v_mfma_f32_16x16x32_bf16 v[52:55], v[152:155], v[184:187], v[52:55]
	v_mfma_f32_16x16x32_bf16 v[52:55], v[156:159], v[188:191], v[52:55]
	v_mfma_f32_16x16x32_bf16 v[56:59], v[160:163], v[184:187], v[56:59]
	v_mfma_f32_16x16x32_bf16 v[56:59], v[164:167], v[188:191], v[56:59]
	v_mfma_f32_16x16x32_bf16 v[60:63], v[152:155], v[192:195], v[60:63]
	v_mfma_f32_16x16x32_bf16 v[60:63], v[156:159], v[196:199], v[60:63]
	v_mfma_f32_16x16x32_bf16 v[64:67], v[160:163], v[192:195], v[64:67]
	v_mfma_f32_16x16x32_bf16 v[64:67], v[164:167], v[196:199], v[64:67]
	s_setprio 0
	s_barrier
	s_mov_b32 m0, s59
	s_nop 0
	global_load_lds_dwordx4 v2, s[100:101]
	s_mov_b32 m0, s42
	s_mov_b64 s[8:9], s[18:19]
	ds_read_b128 v[168:171], v244 offset:49152
	ds_read_b128 v[172:175], v244 offset:50176
	ds_read_b128 v[176:179], v244 offset:51200
	ds_read_b128 v[180:183], v244 offset:52224
	ds_read_b128 v[184:187], v244 offset:53248
	ds_read_b128 v[188:191], v244 offset:54272
	ds_read_b128 v[192:195], v244 offset:55296
	ds_read_b128 v[196:199], v244 offset:56320
	s_nop 0
	global_load_lds_dwordx4 v246, s[8:9]
	s_mov_b32 m0, s43
	s_nop 0
	global_load_lds_dwordx4 v245, s[8:9]
	s_add_u32 s8, s18, s28
	s_addc_u32 s9, s19, s29
	s_mov_b32 m0, s76
	s_nop 0
	global_load_lds_dwordx4 v246, s[8:9]
	s_mov_b32 m0, s77
	s_nop 0
	global_load_lds_dwordx4 v245, s[8:9]
	s_waitcnt vmcnt(6)
	s_waitcnt lgkmcnt(0)
	s_barrier
	s_setprio 1
	s_waitcnt lgkmcnt(0)
	v_mfma_f32_16x16x32_bf16 v[68:71], v[136:139], v[168:171], v[68:71]
	v_mfma_f32_16x16x32_bf16 v[68:71], v[140:143], v[172:175], v[68:71]
	v_mfma_f32_16x16x32_bf16 v[72:75], v[144:147], v[168:171], v[72:75]
	v_mfma_f32_16x16x32_bf16 v[72:75], v[148:151], v[172:175], v[72:75]
	v_mfma_f32_16x16x32_bf16 v[76:79], v[136:139], v[176:179], v[76:79]
	v_mfma_f32_16x16x32_bf16 v[76:79], v[140:143], v[180:183], v[76:79]
	v_mfma_f32_16x16x32_bf16 v[80:83], v[144:147], v[176:179], v[80:83]
	v_mfma_f32_16x16x32_bf16 v[80:83], v[148:151], v[180:183], v[80:83]
	v_mfma_f32_16x16x32_bf16 v[84:87], v[136:139], v[184:187], v[84:87]
	v_mfma_f32_16x16x32_bf16 v[84:87], v[140:143], v[188:191], v[84:87]
	v_mfma_f32_16x16x32_bf16 v[88:91], v[144:147], v[184:187], v[88:91]
	v_mfma_f32_16x16x32_bf16 v[88:91], v[148:151], v[188:191], v[88:91]
	v_mfma_f32_16x16x32_bf16 v[92:95], v[136:139], v[192:195], v[92:95]
	v_mfma_f32_16x16x32_bf16 v[92:95], v[140:143], v[196:199], v[92:95]
	v_mfma_f32_16x16x32_bf16 v[96:99], v[144:147], v[192:195], v[96:99]
	v_mfma_f32_16x16x32_bf16 v[96:99], v[148:151], v[196:199], v[96:99]
	s_setprio 0
	s_setprio 1
	v_mfma_f32_16x16x32_bf16 v[100:103], v[152:155], v[168:171], v[100:103]
	v_mfma_f32_16x16x32_bf16 v[100:103], v[156:159], v[172:175], v[100:103]
	v_mfma_f32_16x16x32_bf16 v[104:107], v[160:163], v[168:171], v[104:107]
	v_mfma_f32_16x16x32_bf16 v[104:107], v[164:167], v[172:175], v[104:107]
	v_mfma_f32_16x16x32_bf16 v[108:111], v[152:155], v[176:179], v[108:111]
	v_mfma_f32_16x16x32_bf16 v[108:111], v[156:159], v[180:183], v[108:111]
	v_mfma_f32_16x16x32_bf16 v[112:115], v[160:163], v[176:179], v[112:115]
	v_mfma_f32_16x16x32_bf16 v[112:115], v[164:167], v[180:183], v[112:115]
	v_mfma_f32_16x16x32_bf16 v[116:119], v[152:155], v[184:187], v[116:119]
	v_mfma_f32_16x16x32_bf16 v[116:119], v[156:159], v[188:191], v[116:119]
	v_mfma_f32_16x16x32_bf16 v[120:123], v[160:163], v[184:187], v[120:123]
	v_mfma_f32_16x16x32_bf16 v[120:123], v[164:167], v[188:191], v[120:123]
	v_mfma_f32_16x16x32_bf16 v[124:127], v[152:155], v[192:195], v[124:127]
	v_mfma_f32_16x16x32_bf16 v[124:127], v[156:159], v[196:199], v[124:127]
	v_mfma_f32_16x16x32_bf16 v[128:131], v[160:163], v[192:195], v[128:131]
	v_mfma_f32_16x16x32_bf16 v[128:131], v[164:167], v[196:199], v[128:131]
	s_setprio 0
	s_barrier
	s_add_i32 s8, s80, 2
	s_add_u32 s78, s78, 0x100
	s_addc_u32 s79, s79, 0
	s_add_u32 s50, s50, 0x100
	s_addc_u32 s51, s51, 0
	s_cmp_ge_i32 s80, s6
	s_mov_b32 s80, s8
	s_cbranch_scc0 .LBB0_1176
